# sample-row small GEMMs staged through LDS with quad-contiguous LDS-DMA loads (were per-lane strided loads into MFMA layout)
# speedup vs baseline: 1.0336x; 1.0154x over previous
; #define LAS __attribute__((address_space(3)))
; __device__ __forceinline__ void small_gemm_q256(LAS unsigned char* lds, const bf16_t* A, const bf16_t* Bt, int unit, const float* SS, float sc, bf16_t* OUT) {
;     int tid = threadIdx.x; asm volatile("" : "+v"(tid));
;     const int wave = __builtin_amdgcn_readfirstlane(tid >> 6), lane = tid & 63, li = lane & 15, g4 = lane >> 4;
;     const int rt = unit >> 2, ct = unit & 3, row0 = TP + 16 * rt, col0 = 256 * ct;
;     constexpr int K = D, KS = 4;
;     const int row = tid >> 5;
;     f32x4 sv[4];
; #pragma unroll
;     for (int q = 0; q < 4; ++q) sv[q] = ((const f32x4*)(SS + (size_t)(row0 + row) * 16))[q];
;     f32x4 acc[16];
; #pragma unroll
;     for (int t = 0; t < 16; ++t) acc[t] = (f32x4){0.f, 0.f, 0.f, 0.f};
;     const bf16_t* ap = A + (size_t)(row0 + li) * K + 8 * g4 + 32 * wave * KS;
;     const bf16_t* bp = Bt + (size_t)(col0 + li) * K + 8 * g4 + 32 * wave * KS;
; #pragma unroll 2
;     for (int ks = 0; ks < KS; ++ks) {
;         const bf16x8 a = *(const bf16x8*)(ap + 32 * ks);
; #pragma unroll
;         for (int t = 0; t < 16; ++t) { const bf16x8 b = *(const bf16x8*)(bp + (size_t)16 * t * K + 32 * ks); acc[t] = __builtin_amdgcn_mfma_f32_16x16x32_bf16(b, a, acc[t], 0, 0, 0); }
.LBB0_586:
	v_mov_b32_e32 v112, v208
	s_and_b32 s4, s12, -16
	v_readfirstlane_b32 s0, v112
	s_ashr_i32 s3, s0, 6
	s_lshl_b32 s0, s14, 2
	s_and_b32 s0, s0, -16
	s_addk_i32 s0, 0x4000
	v_ashrrev_i32_e32 v113, 5, v112
	v_add_u32_e32 v82, s0, v113
	v_ashrrev_i32_e32 v83, 31, v82
	v_lshlrev_b64 v[2:3], 6, v[82:83]
	v_lshl_add_u64 v[2:3], s[10:11], 0, v[2:3]
	global_load_dwordx4 v[14:17], v[2:3], off
	global_load_dwordx4 v[10:13], v[2:3], off offset:16
	global_load_dwordx4 v[6:9], v[2:3], off offset:32
	s_nop 0
	global_load_dwordx4 v[2:5], v[2:3], off offset:48
	v_and_b32_e32 v0, 15, v112
	s_lshl_b32 s0, s3, 7
	s_addk_i32 s4, 0x4000
	s_ashr_i32 s1, s0, 31
	v_or_b32_e32 v18, s4, v0
	s_lshr_b32 s2, s13, 8
	v_ashrrev_i32_e32 v19, 31, v18
	s_lshl_b64 s[0:1], s[0:1], 1
	v_lshlrev_b64 v[18:19], 11, v[18:19]
	v_and_b32_e32 v20, 48, v112
	s_add_u32 s4, s22, s0
	v_or_b32_e32 v18, v18, v20
	s_addc_u32 s5, s23, s1
	v_lshl_add_u64 v[84:85], s[4:5], 0, v[18:19]
	v_or_b32_e32 v18, s0, v20
	s_lshl_b32 s0, s13, 11
	s_and_b32 s0, s0, 0x180000
	v_mov_b32_e32 v19, s1
	v_lshlrev_b32_e32 v115, 10, v0
	v_lshl_or_b32 v0, v0, 11, s0
	v_lshl_add_u64 v[18:19], v[18:19], 0, v[0:1]
	v_lshl_add_u64 v[86:87], s[20:21], 0, v[18:19]
	v_mov_b32_e32 v18, 0
	s_mov_b32 s19, s47
	s_mov_b32 s18, s45
	v_lshrrev_b32_e32 v114, 4, v112
	s_mov_b64 s[0:1], 0
	v_mov_b32_e32 v19, v18
	v_mov_b32_e32 v20, v18
	v_mov_b32_e32 v21, v18
	v_mov_b32_e32 v22, v18
	v_mov_b32_e32 v23, v18
	v_mov_b32_e32 v24, v18
	v_mov_b32_e32 v25, v18
	v_mov_b32_e32 v26, v18
	v_mov_b32_e32 v27, v18
	v_mov_b32_e32 v28, v18
	v_mov_b32_e32 v29, v18
	v_mov_b32_e32 v30, v18
	v_mov_b32_e32 v31, v18
	v_mov_b32_e32 v32, v18
	v_mov_b32_e32 v33, v18
	v_mov_b32_e32 v34, v18
	v_mov_b32_e32 v35, v18
	v_mov_b32_e32 v36, v18
	v_mov_b32_e32 v37, v18
	v_mov_b32_e32 v38, v18
	v_mov_b32_e32 v39, v18
	v_mov_b32_e32 v40, v18
	v_mov_b32_e32 v41, v18
	v_mov_b32_e32 v42, v18
	v_mov_b32_e32 v43, v18
	v_mov_b32_e32 v44, v18
	v_mov_b32_e32 v45, v18
	v_mov_b32_e32 v50, v18
	v_mov_b32_e32 v51, v18
	v_mov_b32_e32 v52, v18
	v_mov_b32_e32 v53, v18
	v_mov_b32_e32 v54, v18
	v_mov_b32_e32 v55, v18
	v_mov_b32_e32 v56, v18
	v_mov_b32_e32 v57, v18
	v_mov_b32_e32 v58, v18
	v_mov_b32_e32 v59, v18
	v_mov_b32_e32 v60, v18
	v_mov_b32_e32 v61, v18
	v_mov_b32_e32 v62, v18
	v_mov_b32_e32 v63, v18
	v_mov_b32_e32 v64, v18
	v_mov_b32_e32 v65, v18
	v_mov_b32_e32 v66, v18
	v_mov_b32_e32 v67, v18
	v_mov_b32_e32 v68, v18
	v_mov_b32_e32 v69, v18
	v_mov_b32_e32 v70, v18
	v_mov_b32_e32 v71, v18
	v_mov_b32_e32 v72, v18
	v_mov_b32_e32 v73, v18
	v_mov_b32_e32 v74, v18
	v_mov_b32_e32 v75, v18
	v_mov_b32_e32 v76, v18
	v_mov_b32_e32 v77, v18
	v_mov_b32_e32 v78, v18
	v_mov_b32_e32 v79, v18
	v_mov_b32_e32 v80, v18
	v_mov_b32_e32 v81, v18
	v_mov_b32_e32 v46, v18
	v_mov_b32_e32 v47, v18
	v_mov_b32_e32 v48, v18
	v_mov_b32_e32 v49, v18
	v_bfe_u32 v132, v112, 2, 4
	v_and_b32_e32 v133, 15, v112
	v_sub_u32_e32 v132, v132, v133
	v_lshlrev_b32_e32 v132, 11, v132
	v_and_b32_e32 v134, 3, v112
	v_lshlrev_b32_e32 v134, 4, v134
	v_and_b32_e32 v135, 48, v112
	v_sub_u32_e32 v134, v134, v135
	v_add_u32_e32 v132, v132, v134
	v_ashrrev_i32_e32 v133, 31, v132
	v_lshl_add_u64 v[84:85], v[84:85], 0, v[132:133]
	v_lshl_add_u64 v[86:87], v[86:87], 0, v[132:133]
	s_lshl_b32 s4, s3, 14
	v_and_b32_e32 v136, 15, v112
	v_lshl_add_u32 v136, v136, 6, v135
	v_add_u32_e32 v136, s4, v136
	s_mov_b64 s[0:1], 0x8000
	s_add_i32 m0, s4, 0x0
	s_nop 0
	global_load_lds_dwordx4 v[84:85], off
	v_lshl_add_u64 v[84:85], v[84:85], 0, 64
	s_add_i32 m0, s4, 0x400
	s_nop 0
	global_load_lds_dwordx4 v[86:87], off
	s_add_i32 m0, s4, 0x800
	v_lshl_add_u64 v[144:145], v[86:87], 0, s[0:1]
	global_load_lds_dwordx4 v[144:145], off
	s_add_i32 m0, s4, 0xc00
	v_lshl_add_u64 v[146:147], v[144:145], 0, s[0:1]
	global_load_lds_dwordx4 v[146:147], off
	s_add_i32 m0, s4, 0x1000
	v_lshl_add_u64 v[144:145], v[146:147], 0, s[0:1]
	global_load_lds_dwordx4 v[144:145], off
	s_add_i32 m0, s4, 0x1400
	v_lshl_add_u64 v[146:147], v[144:145], 0, s[0:1]
	global_load_lds_dwordx4 v[146:147], off
	s_add_i32 m0, s4, 0x1800
	v_lshl_add_u64 v[144:145], v[146:147], 0, s[0:1]
	global_load_lds_dwordx4 v[144:145], off
	s_add_i32 m0, s4, 0x1c00
	v_lshl_add_u64 v[146:147], v[144:145], 0, s[0:1]
	global_load_lds_dwordx4 v[146:147], off
	s_add_i32 m0, s4, 0x2000
	v_lshl_add_u64 v[144:145], v[146:147], 0, s[0:1]
	global_load_lds_dwordx4 v[144:145], off
	s_add_i32 m0, s4, 0x2400
	v_lshl_add_u64 v[146:147], v[144:145], 0, s[0:1]
	global_load_lds_dwordx4 v[146:147], off
	s_add_i32 m0, s4, 0x2800
	v_lshl_add_u64 v[144:145], v[146:147], 0, s[0:1]
	global_load_lds_dwordx4 v[144:145], off
	s_add_i32 m0, s4, 0x2c00
	v_lshl_add_u64 v[146:147], v[144:145], 0, s[0:1]
	global_load_lds_dwordx4 v[146:147], off
	s_add_i32 m0, s4, 0x3000
	v_lshl_add_u64 v[144:145], v[146:147], 0, s[0:1]
	global_load_lds_dwordx4 v[144:145], off
	s_add_i32 m0, s4, 0x3400
	v_lshl_add_u64 v[146:147], v[144:145], 0, s[0:1]
	global_load_lds_dwordx4 v[146:147], off
	s_add_i32 m0, s4, 0x3800
	v_lshl_add_u64 v[144:145], v[146:147], 0, s[0:1]
	global_load_lds_dwordx4 v[144:145], off
	s_add_i32 m0, s4, 0x3c00
	v_lshl_add_u64 v[146:147], v[144:145], 0, s[0:1]
	global_load_lds_dwordx4 v[146:147], off
	s_waitcnt vmcnt(11)
	ds_read_b128 v[88:91], v136 offset:0
	ds_read_b128 v[96:99], v136 offset:1024
	ds_read_b128 v[100:103], v136 offset:2048
	ds_read_b128 v[104:107], v136 offset:3072
	ds_read_b128 v[108:111], v136 offset:4096
	s_waitcnt vmcnt(7)
	ds_read_b128 v[116:119], v136 offset:5120
	ds_read_b128 v[120:123], v136 offset:6144
	ds_read_b128 v[124:127], v136 offset:7168
	ds_read_b128 v[128:131], v136 offset:8192
	s_waitcnt lgkmcnt(4)
; __device__ __forceinline__ void small_gemm_q256(LAS unsigned char* lds, const bf16_t* A, const bf16_t* Bt, int unit, const float* SS, float sc, bf16_t* OUT) {
;     ...
; #pragma unroll 2
;     for (int ks = 0; ks < KS; ++ks) {
;         const bf16x8 a = *(const bf16x8*)(ap + 32 * ks);
; #pragma unroll
;         for (int t = 0; t < 16; ++t) { const bf16x8 b = *(const bf16x8*)(bp + (size_t)16 * t * K + 32 * ks); acc[t] = __builtin_amdgcn_mfma_f32_16x16x32_bf16(b, a, acc[t], 0, 0, 0); }
	v_mfma_f32_16x16x32_bf16 v[46:49], v[96:99], v[88:91], v[46:49]
	v_mfma_f32_16x16x32_bf16 v[78:81], v[100:103], v[88:91], v[78:81]
	v_mfma_f32_16x16x32_bf16 v[74:77], v[104:107], v[88:91], v[74:77]
	v_mfma_f32_16x16x32_bf16 v[70:73], v[108:111], v[88:91], v[70:73]
	s_add_i32 m0, s4, 0x0
	v_lshl_add_u64 v[144:145], v[146:147], 0, s[0:1]
	global_load_lds_dwordx4 v[144:145], off
	v_lshl_add_u64 v[86:87], v[86:87], 0, 64
	s_add_i32 m0, s4, 0x400
	s_nop 0
	global_load_lds_dwordx4 v[84:85], off
	v_lshl_add_u64 v[84:85], v[84:85], 0, 64
	s_add_i32 m0, s4, 0x800
	s_nop 0
	global_load_lds_dwordx4 v[86:87], off
	s_add_i32 m0, s4, 0xc00
	v_lshl_add_u64 v[144:145], v[86:87], 0, s[0:1]
	global_load_lds_dwordx4 v[144:145], off
	s_add_i32 m0, s4, 0x1000
	v_lshl_add_u64 v[146:147], v[144:145], 0, s[0:1]
	global_load_lds_dwordx4 v[146:147], off
	s_waitcnt vmcnt(8)
	ds_read_b128 v[96:99], v136 offset:9216
	ds_read_b128 v[100:103], v136 offset:10240
	ds_read_b128 v[104:107], v136 offset:11264
	ds_read_b128 v[108:111], v136 offset:12288
	s_waitcnt lgkmcnt(4)
	v_mfma_f32_16x16x32_bf16 v[66:69], v[116:119], v[88:91], v[66:69]
	v_mfma_f32_16x16x32_bf16 v[62:65], v[120:123], v[88:91], v[62:65]
	v_mfma_f32_16x16x32_bf16 v[58:61], v[124:127], v[88:91], v[58:61]
	v_mfma_f32_16x16x32_bf16 v[54:57], v[128:131], v[88:91], v[54:57]
	s_add_i32 m0, s4, 0x1400
	v_lshl_add_u64 v[144:145], v[146:147], 0, s[0:1]
	global_load_lds_dwordx4 v[144:145], off
	s_add_i32 m0, s4, 0x1800
	v_lshl_add_u64 v[146:147], v[144:145], 0, s[0:1]
	global_load_lds_dwordx4 v[146:147], off
	s_add_i32 m0, s4, 0x1c00
	v_lshl_add_u64 v[144:145], v[146:147], 0, s[0:1]
	global_load_lds_dwordx4 v[144:145], off
	s_add_i32 m0, s4, 0x2000
	v_lshl_add_u64 v[146:147], v[144:145], 0, s[0:1]
	global_load_lds_dwordx4 v[146:147], off
	s_waitcnt vmcnt(8)
	ds_read_b128 v[116:119], v136 offset:13312
	ds_read_b128 v[120:123], v136 offset:14336
	ds_read_b128 v[124:127], v136 offset:15360
	ds_read_b128 v[128:131], v136 offset:0
	s_waitcnt lgkmcnt(4)
	v_mfma_f32_16x16x32_bf16 v[50:53], v[96:99], v[88:91], v[50:53]
	v_mfma_f32_16x16x32_bf16 v[42:45], v[100:103], v[88:91], v[42:45]
	v_mfma_f32_16x16x32_bf16 v[38:41], v[104:107], v[88:91], v[38:41]
	v_mfma_f32_16x16x32_bf16 v[34:37], v[108:111], v[88:91], v[34:37]
	s_add_i32 m0, s4, 0x2400
	v_lshl_add_u64 v[144:145], v[146:147], 0, s[0:1]
	global_load_lds_dwordx4 v[144:145], off
	s_add_i32 m0, s4, 0x2800
	v_lshl_add_u64 v[146:147], v[144:145], 0, s[0:1]
	global_load_lds_dwordx4 v[146:147], off
	s_add_i32 m0, s4, 0x2c00
	v_lshl_add_u64 v[144:145], v[146:147], 0, s[0:1]
	global_load_lds_dwordx4 v[144:145], off
	s_add_i32 m0, s4, 0x3000
	v_lshl_add_u64 v[146:147], v[144:145], 0, s[0:1]
	global_load_lds_dwordx4 v[146:147], off
	s_waitcnt vmcnt(7)
	ds_read_b128 v[92:95], v136 offset:1024
	ds_read_b128 v[96:99], v136 offset:2048
	ds_read_b128 v[100:103], v136 offset:3072
	ds_read_b128 v[104:107], v136 offset:4096
	ds_read_b128 v[108:111], v136 offset:5120
	s_waitcnt lgkmcnt(5)
	v_mfma_f32_16x16x32_bf16 v[30:33], v[116:119], v[88:91], v[30:33]
	v_mfma_f32_16x16x32_bf16 v[26:29], v[120:123], v[88:91], v[26:29]
	v_mfma_f32_16x16x32_bf16 v[22:25], v[124:127], v[88:91], v[22:25]
	v_mfma_f32_16x16x32_bf16 v[18:21], v[128:131], v[88:91], v[18:21]
	s_add_i32 m0, s4, 0x3400
	v_lshl_add_u64 v[144:145], v[146:147], 0, s[0:1]
	global_load_lds_dwordx4 v[144:145], off
	s_add_i32 m0, s4, 0x3800
	v_lshl_add_u64 v[146:147], v[144:145], 0, s[0:1]
	global_load_lds_dwordx4 v[146:147], off
	s_add_i32 m0, s4, 0x3c00
	v_lshl_add_u64 v[144:145], v[146:147], 0, s[0:1]
	global_load_lds_dwordx4 v[144:145], off
	s_add_i32 m0, s4, 0x0
	v_lshl_add_u64 v[146:147], v[144:145], 0, s[0:1]
	global_load_lds_dwordx4 v[146:147], off
	s_waitcnt vmcnt(7)
	ds_read_b128 v[116:119], v136 offset:6144
	ds_read_b128 v[120:123], v136 offset:7168
	ds_read_b128 v[124:127], v136 offset:8192
	ds_read_b128 v[128:131], v136 offset:9216
	s_waitcnt lgkmcnt(4)
	v_mfma_f32_16x16x32_bf16 v[46:49], v[96:99], v[92:95], v[46:49]
	v_mfma_f32_16x16x32_bf16 v[78:81], v[100:103], v[92:95], v[78:81]
	v_mfma_f32_16x16x32_bf16 v[74:77], v[104:107], v[92:95], v[74:77]
	v_mfma_f32_16x16x32_bf16 v[70:73], v[108:111], v[92:95], v[70:73]
	s_add_i32 m0, s4, 0x400
	v_lshl_add_u64 v[144:145], v[146:147], 0, s[0:1]
	global_load_lds_dwordx4 v[144:145], off
	v_lshl_add_u64 v[86:87], v[86:87], 0, 64
	s_add_i32 m0, s4, 0x800
	s_nop 0
	global_load_lds_dwordx4 v[84:85], off
	v_lshl_add_u64 v[84:85], v[84:85], 0, 64
	s_add_i32 m0, s4, 0xc00
	s_nop 0
	global_load_lds_dwordx4 v[86:87], off
	s_add_i32 m0, s4, 0x1000
	v_lshl_add_u64 v[144:145], v[86:87], 0, s[0:1]
	global_load_lds_dwordx4 v[144:145], off
	s_add_i32 m0, s4, 0x1400
	v_lshl_add_u64 v[146:147], v[144:145], 0, s[0:1]
	global_load_lds_dwordx4 v[146:147], off
	s_waitcnt vmcnt(8)
	ds_read_b128 v[96:99], v136 offset:10240
	ds_read_b128 v[100:103], v136 offset:11264
	ds_read_b128 v[104:107], v136 offset:12288
	ds_read_b128 v[108:111], v136 offset:13312
	s_waitcnt lgkmcnt(4)
	v_mfma_f32_16x16x32_bf16 v[66:69], v[116:119], v[92:95], v[66:69]
	v_mfma_f32_16x16x32_bf16 v[62:65], v[120:123], v[92:95], v[62:65]
	v_mfma_f32_16x16x32_bf16 v[58:61], v[124:127], v[92:95], v[58:61]
	v_mfma_f32_16x16x32_bf16 v[54:57], v[128:131], v[92:95], v[54:57]
	s_add_i32 m0, s4, 0x1800
	v_lshl_add_u64 v[144:145], v[146:147], 0, s[0:1]
	global_load_lds_dwordx4 v[144:145], off
	s_add_i32 m0, s4, 0x1c00
	v_lshl_add_u64 v[146:147], v[144:145], 0, s[0:1]
	global_load_lds_dwordx4 v[146:147], off
	s_add_i32 m0, s4, 0x2000
	v_lshl_add_u64 v[144:145], v[146:147], 0, s[0:1]
	global_load_lds_dwordx4 v[144:145], off
	s_add_i32 m0, s4, 0x2400
	v_lshl_add_u64 v[146:147], v[144:145], 0, s[0:1]
	global_load_lds_dwordx4 v[146:147], off
	s_waitcnt vmcnt(8)
; __device__ __forceinline__ void small_gemm_q256(LAS unsigned char* lds, const bf16_t* A, const bf16_t* Bt, int unit, const float* SS, float sc, bf16_t* OUT) {
;     ...
; #pragma unroll 2
;     for (int ks = 0; ks < KS; ++ks) {
;         const bf16x8 a = *(const bf16x8*)(ap + 32 * ks);
; #pragma unroll
;         for (int t = 0; t < 16; ++t) { const bf16x8 b = *(const bf16x8*)(bp + (size_t)16 * t * K + 32 * ks); acc[t] = __builtin_amdgcn_mfma_f32_16x16x32_bf16(b, a, acc[t], 0, 0, 0); }
	ds_read_b128 v[116:119], v136 offset:14336
	ds_read_b128 v[120:123], v136 offset:15360
	ds_read_b128 v[124:127], v136 offset:0
	ds_read_b128 v[128:131], v136 offset:1024
	s_waitcnt lgkmcnt(4)
	v_mfma_f32_16x16x32_bf16 v[50:53], v[96:99], v[92:95], v[50:53]
	v_mfma_f32_16x16x32_bf16 v[42:45], v[100:103], v[92:95], v[42:45]
	v_mfma_f32_16x16x32_bf16 v[38:41], v[104:107], v[92:95], v[38:41]
	v_mfma_f32_16x16x32_bf16 v[34:37], v[108:111], v[92:95], v[34:37]
	s_add_i32 m0, s4, 0x2800
	v_lshl_add_u64 v[144:145], v[146:147], 0, s[0:1]
	global_load_lds_dwordx4 v[144:145], off
	s_add_i32 m0, s4, 0x2c00
	v_lshl_add_u64 v[146:147], v[144:145], 0, s[0:1]
	global_load_lds_dwordx4 v[146:147], off
	s_add_i32 m0, s4, 0x3000
	v_lshl_add_u64 v[144:145], v[146:147], 0, s[0:1]
	global_load_lds_dwordx4 v[144:145], off
	s_add_i32 m0, s4, 0x3400
	v_lshl_add_u64 v[146:147], v[144:145], 0, s[0:1]
	global_load_lds_dwordx4 v[146:147], off
	s_waitcnt vmcnt(7)
	ds_read_b128 v[88:91], v136 offset:2048
	ds_read_b128 v[96:99], v136 offset:3072
	ds_read_b128 v[100:103], v136 offset:4096
	ds_read_b128 v[104:107], v136 offset:5120
	ds_read_b128 v[108:111], v136 offset:6144
	s_waitcnt lgkmcnt(5)
	v_mfma_f32_16x16x32_bf16 v[30:33], v[116:119], v[92:95], v[30:33]
	v_mfma_f32_16x16x32_bf16 v[26:29], v[120:123], v[92:95], v[26:29]
	v_mfma_f32_16x16x32_bf16 v[22:25], v[124:127], v[92:95], v[22:25]
	v_mfma_f32_16x16x32_bf16 v[18:21], v[128:131], v[92:95], v[18:21]
	s_add_i32 m0, s4, 0x3800
	v_lshl_add_u64 v[144:145], v[146:147], 0, s[0:1]
	global_load_lds_dwordx4 v[144:145], off
	s_add_i32 m0, s4, 0x3c00
	v_lshl_add_u64 v[146:147], v[144:145], 0, s[0:1]
	global_load_lds_dwordx4 v[146:147], off
	s_add_i32 m0, s4, 0x0
	v_lshl_add_u64 v[144:145], v[146:147], 0, s[0:1]
	global_load_lds_dwordx4 v[144:145], off
	s_add_i32 m0, s4, 0x400
	v_lshl_add_u64 v[146:147], v[144:145], 0, s[0:1]
	global_load_lds_dwordx4 v[146:147], off
	s_waitcnt vmcnt(7)
	ds_read_b128 v[116:119], v136 offset:7168
	ds_read_b128 v[120:123], v136 offset:8192
	ds_read_b128 v[124:127], v136 offset:9216
	ds_read_b128 v[128:131], v136 offset:10240
	s_waitcnt lgkmcnt(4)
	v_mfma_f32_16x16x32_bf16 v[46:49], v[96:99], v[88:91], v[46:49]
	v_mfma_f32_16x16x32_bf16 v[78:81], v[100:103], v[88:91], v[78:81]
	v_mfma_f32_16x16x32_bf16 v[74:77], v[104:107], v[88:91], v[74:77]
	v_mfma_f32_16x16x32_bf16 v[70:73], v[108:111], v[88:91], v[70:73]
	s_add_i32 m0, s4, 0x800
	v_lshl_add_u64 v[144:145], v[146:147], 0, s[0:1]
	global_load_lds_dwordx4 v[144:145], off
	v_lshl_add_u64 v[86:87], v[86:87], 0, 64
	s_add_i32 m0, s4, 0xc00
	s_nop 0
	global_load_lds_dwordx4 v[84:85], off
	v_lshl_add_u64 v[84:85], v[84:85], 0, 64
	s_add_i32 m0, s4, 0x1000
	s_nop 0
	global_load_lds_dwordx4 v[86:87], off
	s_add_i32 m0, s4, 0x1400
	v_lshl_add_u64 v[144:145], v[86:87], 0, s[0:1]
	global_load_lds_dwordx4 v[144:145], off
	s_add_i32 m0, s4, 0x1800
	v_lshl_add_u64 v[146:147], v[144:145], 0, s[0:1]
	global_load_lds_dwordx4 v[146:147], off
	s_waitcnt vmcnt(8)
	ds_read_b128 v[96:99], v136 offset:11264
	ds_read_b128 v[100:103], v136 offset:12288
	ds_read_b128 v[104:107], v136 offset:13312
	ds_read_b128 v[108:111], v136 offset:14336
	s_waitcnt lgkmcnt(4)
	v_mfma_f32_16x16x32_bf16 v[66:69], v[116:119], v[88:91], v[66:69]
	v_mfma_f32_16x16x32_bf16 v[62:65], v[120:123], v[88:91], v[62:65]
	v_mfma_f32_16x16x32_bf16 v[58:61], v[124:127], v[88:91], v[58:61]
	v_mfma_f32_16x16x32_bf16 v[54:57], v[128:131], v[88:91], v[54:57]
	s_add_i32 m0, s4, 0x1c00
	v_lshl_add_u64 v[144:145], v[146:147], 0, s[0:1]
	global_load_lds_dwordx4 v[144:145], off
	s_add_i32 m0, s4, 0x2000
	v_lshl_add_u64 v[146:147], v[144:145], 0, s[0:1]
	global_load_lds_dwordx4 v[146:147], off
	s_add_i32 m0, s4, 0x2400
	v_lshl_add_u64 v[144:145], v[146:147], 0, s[0:1]
	global_load_lds_dwordx4 v[144:145], off
	s_add_i32 m0, s4, 0x2800
	v_lshl_add_u64 v[146:147], v[144:145], 0, s[0:1]
	global_load_lds_dwordx4 v[146:147], off
	s_waitcnt vmcnt(8)
	ds_read_b128 v[116:119], v136 offset:15360
	ds_read_b128 v[120:123], v136 offset:0
	ds_read_b128 v[124:127], v136 offset:1024
	ds_read_b128 v[128:131], v136 offset:2048
	s_waitcnt lgkmcnt(4)
	v_mfma_f32_16x16x32_bf16 v[50:53], v[96:99], v[88:91], v[50:53]
	v_mfma_f32_16x16x32_bf16 v[42:45], v[100:103], v[88:91], v[42:45]
	v_mfma_f32_16x16x32_bf16 v[38:41], v[104:107], v[88:91], v[38:41]
	v_mfma_f32_16x16x32_bf16 v[34:37], v[108:111], v[88:91], v[34:37]
	s_add_i32 m0, s4, 0x2c00
	v_lshl_add_u64 v[144:145], v[146:147], 0, s[0:1]
	global_load_lds_dwordx4 v[144:145], off
	s_add_i32 m0, s4, 0x3000
	v_lshl_add_u64 v[146:147], v[144:145], 0, s[0:1]
	global_load_lds_dwordx4 v[146:147], off
	s_add_i32 m0, s4, 0x3400
	v_lshl_add_u64 v[144:145], v[146:147], 0, s[0:1]
	global_load_lds_dwordx4 v[144:145], off
	s_add_i32 m0, s4, 0x3800
	v_lshl_add_u64 v[146:147], v[144:145], 0, s[0:1]
	global_load_lds_dwordx4 v[146:147], off
	s_waitcnt vmcnt(7)
	ds_read_b128 v[92:95], v136 offset:3072
	ds_read_b128 v[96:99], v136 offset:4096
	ds_read_b128 v[100:103], v136 offset:5120
	ds_read_b128 v[104:107], v136 offset:6144
	ds_read_b128 v[108:111], v136 offset:7168
	s_waitcnt lgkmcnt(5)
	v_mfma_f32_16x16x32_bf16 v[30:33], v[116:119], v[88:91], v[30:33]
	v_mfma_f32_16x16x32_bf16 v[26:29], v[120:123], v[88:91], v[26:29]
	v_mfma_f32_16x16x32_bf16 v[22:25], v[124:127], v[88:91], v[22:25]
	v_mfma_f32_16x16x32_bf16 v[18:21], v[128:131], v[88:91], v[18:21]
	s_add_i32 m0, s4, 0x3c00
	v_lshl_add_u64 v[144:145], v[146:147], 0, s[0:1]
	global_load_lds_dwordx4 v[144:145], off
	s_add_i32 m0, s4, 0x0
	v_lshl_add_u64 v[146:147], v[144:145], 0, s[0:1]
	global_load_lds_dwordx4 v[146:147], off
	s_add_i32 m0, s4, 0x400
	v_lshl_add_u64 v[144:145], v[146:147], 0, s[0:1]
	global_load_lds_dwordx4 v[144:145], off
	s_add_i32 m0, s4, 0x800
	v_lshl_add_u64 v[146:147], v[144:145], 0, s[0:1]
	global_load_lds_dwordx4 v[146:147], off
	s_waitcnt vmcnt(7)
; #define LAS __attribute__((address_space(3)))
; __device__ __forceinline__ unsigned cvt_pk_bf16(float lo, float hi) { unsigned r; asm("v_cvt_pk_bf16_f32 %0, %1, %2" : "=v"(r) : "v"(lo), "v"(hi)); return r; }
; __device__ __forceinline__ void small_gemm_q256(LAS unsigned char* lds, const bf16_t* A, const bf16_t* Bt, int unit, const float* SS, float sc, bf16_t* OUT) {
;     ...
; #pragma unroll 2
;     for (int ks = 0; ks < KS; ++ks) {
;         const bf16x8 a = *(const bf16x8*)(ap + 32 * ks);
; #pragma unroll
;         for (int t = 0; t < 16; ++t) { const bf16x8 b = *(const bf16x8*)(bp + (size_t)16 * t * K + 32 * ks); acc[t] = __builtin_amdgcn_mfma_f32_16x16x32_bf16(b, a, acc[t], 0, 0, 0); }
;     }
;     LAS float* red = (LAS float*)lds;
; #pragma unroll
;     for (int t = 0; t < 16; ++t) *(LAS f32x4*)(red + (wave * 16 + li) * 256 + 16 * t + 4 * g4) = acc[t];
;     __syncthreads();
;     float sm = 0.f;
; #pragma unroll
;     for (int q = 0; q < 4; ++q) sm += (sv[q][0] + sv[q][1]) + (sv[q][2] + sv[q][3]);
;     const float rs = __builtin_amdgcn_rsqf(sm * (1.0f / 1024.0f) + EPS) * sc;
; #pragma unroll
;     for (int cc = 0; cc < 2; ++cc) {
;         const int c4 = (tid & 31) * 4 + 128 * cc;
;         f32x4 sum = *(LAS f32x4*)(red + row * 256 + c4);
; #pragma unroll
;         for (int w = 1; w < 8; ++w) sum += *(LAS f32x4*)(red + (w * 16 + row) * 256 + c4);
;         u32x2 w; w.x = cvt_pk_bf16(sum[0] * rs, sum[1] * rs); w.y = cvt_pk_bf16(sum[2] * rs, sum[3] * rs);
;         *(u32x2*)(OUT + (size_t)(row0 + row) * D + col0 + c4) = w;
;     }
;     asm volatile("s_waitcnt vmcnt(0)" ::: "memory");
;     __syncthreads();
	ds_read_b128 v[116:119], v136 offset:8192
	ds_read_b128 v[120:123], v136 offset:9216
	ds_read_b128 v[124:127], v136 offset:10240
	ds_read_b128 v[128:131], v136 offset:11264
	s_waitcnt lgkmcnt(4)
	v_mfma_f32_16x16x32_bf16 v[46:49], v[96:99], v[92:95], v[46:49]
	v_mfma_f32_16x16x32_bf16 v[78:81], v[100:103], v[92:95], v[78:81]
	v_mfma_f32_16x16x32_bf16 v[74:77], v[104:107], v[92:95], v[74:77]
	v_mfma_f32_16x16x32_bf16 v[70:73], v[108:111], v[92:95], v[70:73]
	s_add_i32 m0, s4, 0xc00
	v_lshl_add_u64 v[144:145], v[146:147], 0, s[0:1]
	global_load_lds_dwordx4 v[144:145], off
	v_lshl_add_u64 v[86:87], v[86:87], 0, 64
	s_waitcnt vmcnt(4)
	ds_read_b128 v[96:99], v136 offset:12288
	ds_read_b128 v[100:103], v136 offset:13312
	ds_read_b128 v[104:107], v136 offset:14336
	ds_read_b128 v[108:111], v136 offset:15360
	s_waitcnt lgkmcnt(4)
	v_mfma_f32_16x16x32_bf16 v[66:69], v[116:119], v[92:95], v[66:69]
	v_mfma_f32_16x16x32_bf16 v[62:65], v[120:123], v[92:95], v[62:65]
	v_mfma_f32_16x16x32_bf16 v[58:61], v[124:127], v[92:95], v[58:61]
	v_mfma_f32_16x16x32_bf16 v[54:57], v[128:131], v[92:95], v[54:57]
	s_waitcnt vmcnt(0)
	ds_read_b128 v[116:119], v136 offset:0
	ds_read_b128 v[120:123], v136 offset:1024
	ds_read_b128 v[124:127], v136 offset:2048
	ds_read_b128 v[128:131], v136 offset:3072
	s_waitcnt lgkmcnt(4)
	v_mfma_f32_16x16x32_bf16 v[50:53], v[96:99], v[92:95], v[50:53]
	v_mfma_f32_16x16x32_bf16 v[42:45], v[100:103], v[92:95], v[42:45]
	v_mfma_f32_16x16x32_bf16 v[38:41], v[104:107], v[92:95], v[38:41]
	v_mfma_f32_16x16x32_bf16 v[34:37], v[108:111], v[92:95], v[34:37]
	s_waitcnt lgkmcnt(0)
	v_mfma_f32_16x16x32_bf16 v[30:33], v[116:119], v[92:95], v[30:33]
	v_mfma_f32_16x16x32_bf16 v[26:29], v[120:123], v[92:95], v[26:29]
	v_mfma_f32_16x16x32_bf16 v[22:25], v[124:127], v[92:95], v[22:25]
	v_mfma_f32_16x16x32_bf16 v[18:21], v[128:131], v[92:95], v[18:21]
	s_nop 1
	s_lshl_b32 s0, s14, 8
	v_and_b32_e32 v0, 3, v114
	s_and_b32 s15, s0, 0x300
	s_lshl_b32 s0, s3, 14
	s_add_i32 s0, s0, 0
	v_lshlrev_b32_e32 v0, 4, v0
	v_add3_u32 v0, s0, v115, v0
	ds_write_b128 v0, v[46:49]
	ds_write_b128 v0, v[78:81] offset:64
	ds_write_b128 v0, v[74:77] offset:128
	ds_write_b128 v0, v[70:73] offset:192
	ds_write_b128 v0, v[66:69] offset:256
	ds_write_b128 v0, v[62:65] offset:320
	ds_write_b128 v0, v[58:61] offset:384
	ds_write_b128 v0, v[54:57] offset:448
	ds_write_b128 v0, v[50:53] offset:512
	ds_write_b128 v0, v[42:45] offset:576
	ds_write_b128 v0, v[38:41] offset:640
	ds_write_b128 v0, v[34:37] offset:704
	ds_write_b128 v0, v[30:33] offset:768
	ds_write_b128 v0, v[26:29] offset:832
	ds_write_b128 v0, v[22:25] offset:896
	ds_write_b128 v0, v[18:21] offset:960
	v_mov_b32_e32 v18, v15
	v_mov_b32_e32 v19, v16
	v_mov_b32_e32 v15, v17
	v_mov_b32_e32 v16, v11
	v_mov_b32_e32 v17, v12
	v_mov_b32_e32 v11, v13
	v_pk_add_f32 v[14:15], v[18:19], v[14:15]
	v_pk_add_f32 v[10:11], v[16:17], v[10:11]
	v_add_f32_e32 v0, v14, v15
	v_pk_add_f32 v[10:11], v[10:11], v[10:11] op_sel:[0,1] op_sel_hi:[1,0]
	v_add_f32_e32 v14, 0, v0
	v_add_f32_e32 v6, v6, v7
	v_add_f32_e32 v8, v8, v9
	v_mov_b32_e32 v15, v2
	v_mov_b32_e32 v11, v3
	v_mov_b32_e32 v7, v4
	v_mov_b32_e32 v9, v5
	v_pk_add_f32 v[2:3], v[14:15], v[10:11]
	v_pk_add_f32 v[4:5], v[6:7], v[8:9]
	s_waitcnt lgkmcnt(0)
	v_pk_add_f32 v[2:3], v[2:3], v[4:5]
	s_barrier
	v_add_f32_e32 v0, v2, v3
	v_fmamk_f32 v0, v0, 0x3a800000, v209
	v_rsq_f32_e32 v0, v0
	v_lshlrev_b32_e32 v2, 10, v113
	v_lshlrev_b64 v[10:11], 11, v[82:83]
	v_mul_f32_e32 v20, 0x3db8aa3b, v0
	v_lshlrev_b32_e32 v0, 2, v112
	v_and_b32_e32 v0, 0x7c, v0
	v_lshlrev_b32_e32 v3, 2, v0
	v_add3_u32 v21, 0, v2, v3
	ds_read_b128 v[2:5], v21
	ds_read_b128 v[6:9], v21 offset:16384
	v_lshl_add_u64 v[14:15], s[30:31], 0, v[10:11]
	ds_read_b128 v[10:13], v21 offset:32768
	s_lshl_b32 s62, s15, 1
	v_lshl_add_u64 v[14:15], v[14:15], 0, s[62:63]
	s_waitcnt lgkmcnt(1)
	v_pk_add_f32 v[6:7], v[2:3], v[6:7]
	v_pk_add_f32 v[8:9], v[4:5], v[8:9]
	ds_read_b128 v[2:5], v21 offset:49152
	s_waitcnt lgkmcnt(1)
	v_pk_add_f32 v[10:11], v[6:7], v[10:11]
	v_add_u32_e32 v6, 0x10000, v21
	v_pk_add_f32 v[12:13], v[8:9], v[12:13]
	ds_read_b128 v[6:9], v6
	s_waitcnt lgkmcnt(1)
	v_pk_add_f32 v[10:11], v[10:11], v[2:3]
	v_add_u32_e32 v2, 0x14000, v21
	v_pk_add_f32 v[12:13], v[12:13], v[4:5]
	ds_read_b128 v[2:5], v2
	s_waitcnt lgkmcnt(1)
	v_pk_add_f32 v[18:19], v[10:11], v[6:7]
	v_add_u32_e32 v6, 0x18000, v21
	v_pk_add_f32 v[16:17], v[12:13], v[8:9]
	ds_read_b128 v[6:9], v6
	v_add_u32_e32 v10, 0x1c000, v21
	ds_read_b128 v[10:13], v10
	s_waitcnt lgkmcnt(2)
	v_pk_add_f32 v[2:3], v[18:19], v[2:3]
	v_pk_add_f32 v[4:5], v[16:17], v[4:5]
	s_waitcnt lgkmcnt(1)
	v_pk_add_f32 v[2:3], v[2:3], v[6:7]
	v_pk_add_f32 v[4:5], v[4:5], v[8:9]
	s_waitcnt lgkmcnt(0)
	v_pk_add_f32 v[2:3], v[2:3], v[10:11]
	v_pk_add_f32 v[4:5], v[4:5], v[12:13]
	v_mul_f32_e32 v2, v20, v2
	v_mul_f32_e32 v3, v20, v3
	v_lshlrev_b32_e32 v0, 1, v0
	v_cvt_pk_bf16_f32 v2, v2, v3
	v_mul_f32_e32 v3, v20, v4
	v_lshl_add_u64 v[14:15], v[14:15], 0, v[0:1]
	v_mul_f32_e32 v4, v20, v5
	v_cvt_pk_bf16_f32 v3, v3, v4
	flat_store_dwordx2 v[14:15], v[2:3]
	ds_read_b128 v[2:5], v21 offset:512
	ds_read_b128 v[6:9], v21 offset:16896
	ds_read_b128 v[10:13], v21 offset:33280
	v_add_u32_e32 v0, 0x10200, v21
	v_mov_b32_e32 v137, v208
	s_ashr_i32 s17, s14, 2
	s_waitcnt lgkmcnt(0)
	v_pk_add_f32 v[8:9], v[4:5], v[8:9]
	v_pk_add_f32 v[6:7], v[2:3], v[6:7]
	ds_read_b128 v[2:5], v21 offset:49664
	v_pk_add_f32 v[12:13], v[8:9], v[12:13]
	v_pk_add_f32 v[10:11], v[6:7], v[10:11]
	ds_read_b128 v[6:9], v0
	v_add_u32_e32 v0, 0x14200, v21
	s_waitcnt lgkmcnt(0)
	v_pk_add_f32 v[12:13], v[12:13], v[4:5]
	v_pk_add_f32 v[10:11], v[10:11], v[2:3]
	ds_read_b128 v[2:5], v0
	v_add_u32_e32 v0, 0x18200, v21
	v_pk_add_f32 v[16:17], v[12:13], v[8:9]
	v_pk_add_f32 v[18:19], v[10:11], v[6:7]
	ds_read_b128 v[6:9], v0
	v_add_u32_e32 v0, 0x1c200, v21
	ds_read_b128 v[10:13], v0
	s_waitcnt lgkmcnt(0)
	v_pk_add_f32 v[4:5], v[16:17], v[4:5]
	v_pk_add_f32 v[2:3], v[18:19], v[2:3]
	v_pk_add_f32 v[4:5], v[4:5], v[8:9]
	v_pk_add_f32 v[2:3], v[2:3], v[6:7]
	v_pk_add_f32 v[4:5], v[4:5], v[12:13]
	v_pk_add_f32 v[2:3], v[2:3], v[10:11]
	s_and_b32 s16, s2, 3
	v_mul_f32_e32 v0, v20, v2
	v_mul_f32_e32 v2, v20, v3
	v_mul_f32_e32 v3, v20, v5
	v_cvt_pk_bf16_f32 v2, v0, v2
	v_mul_f32_e32 v0, v20, v4
	v_cvt_pk_bf16_f32 v3, v0, v3
	flat_store_dwordx2 v[14:15], v[2:3] offset:256
	s_waitcnt vmcnt(0)
	s_waitcnt lgkmcnt(0)
	s_barrier
; #define LAS __attribute__((address_space(3)))
; __device__ __forceinline__ bf16x8 load8f_bf(const float* p) { const f32x4 a = *(const f32x4*)p, b = *(const f32x4*)(p + 4); return pack8v(a, b); }
; __device__ __forceinline__ int voff_x(int key, int d) { return ((key >> 3) * 8 + (d >> 5)) * 512 + (key & 7) * 64 + (d & 31) * 2; }
; __device__ __forceinline__ void xattn_sample_unit(const Params& P, int l, int b, int h, LAS unsigned char* lds, int tid_) {
;     int tid = tid_; asm volatile("" : "+v"(tid));
;     const int lane = tid & 63, wave = __builtin_amdgcn_readfirstlane(tid >> 6), r = lane & 31, hi = lane >> 5;
;     const bf16_t* Q2 = (const bf16_t*)(P.ws + WS_Q2);
;     bf16_t* O2 = (bf16_t*)(P.ws + WS_O2);
;     const float* CK = P.in[7] + ((size_t)(l * 32 + b) * 256 + 32 * wave) * 1024 + h * 256;
;     const float* CV = P.in[8] + ((size_t)(l * 32 + b) * 256 + 32 * wave) * 1024 + h * 256;
;     LAS unsigned char* wl = lds + wave * 16384;
;     LAS float* ml = (LAS float*)(lds + 131072);
;     const int qrow = TP + b * 16 + (r & 15);
; #pragma unroll 4
;     for (int i = 0; i < 16; ++i) { const int idx = lane + 64 * i, vr = idx >> 5, ch = idx & 31;
;         *(LAS bf16x8*)(wl + voff_x(vr, 8 * ch)) = load8f_bf(CV + (size_t)vr * 1024 + 8 * ch); }
	s_add_i32 s2, s17, s7
	v_readfirstlane_b32 s0, v137
	s_ashr_i32 s4, s0, 6
	s_lshl_b32 s0, s4, 5
	s_ashr_i32 s3, s2, 31
	s_ashr_i32 s1, s0, 31
	s_lshl_b32 s5, s16, 10
	s_lshl_b32 s4, s4, 14
	s_lshl_b64 s[2:3], s[2:3], 20
	s_lshl_b64 s[24:25], s[0:1], 12
	v_lshlrev_b32_e32 v5, 7, v137
	v_lshlrev_b32_e32 v19, 4, v137
	v_bfe_u32 v18, v137, 5, 1
	s_add_u32 s1, s24, s2
	v_and_b32_e32 v136, 31, v137
	v_and_b32_e32 v5, 0xe00, v5
	v_and_b32_e32 v0, 48, v19
	s_addc_u32 s6, s25, s3
	v_lshl_or_b32 v2, v18, 12, s1
	v_lshlrev_b32_e32 v3, 5, v136
	v_readlane_b32 s36, v253, 7
	v_lshlrev_b32_e32 v4, 6, v18
	v_or_b32_e32 v5, s4, v5
	v_or3_b32 v2, v2, s5, v3
	v_mov_b32_e32 v3, s6
	v_readlane_b32 s37, v253, 8
	v_or3_b32 v0, v5, v4, v0
	v_and_b32_e32 v139, 63, v137
	v_lshl_add_u64 v[2:3], s[36:37], 0, v[2:3]
	v_add_u32_e32 v0, 0, v0
	s_mov_b64 s[26:27], 0
	v_readlane_b32 s38, v253, 9
	v_readlane_b32 s39, v253, 10
	v_readlane_b32 s40, v253, 11
	v_readlane_b32 s41, v253, 12
	v_readlane_b32 s42, v253, 13
	v_readlane_b32 s43, v253, 14
	v_readlane_b32 s44, v253, 15
	v_readlane_b32 s45, v253, 16
	v_readlane_b32 s46, v253, 17
	v_readlane_b32 s47, v253, 18
	v_readlane_b32 s48, v253, 19
	v_readlane_b32 s49, v253, 20
	v_readlane_b32 s50, v253, 21
	v_readlane_b32 s51, v253, 22
	v_mov_b32_e32 v128, v2
	v_mov_b32_e32 v129, v3
	v_mov_b32_e32 v138, v0
	s_lshl_b32 s1, s17, 4
	s_lshl_b32 s6, s16, 9
	v_and_b32_e32 v140, 15, v137
	s_addk_i32 s1, 0x4000
	v_or_b32_e32 v2, s1, v140
	s_add_u32 s1, s24, s2
	v_ashrrev_i32_e32 v3, 31, v2
	s_addc_u32 s3, s25, s3
	v_lshlrev_b64 v[134:135], 11, v[2:3]
	v_lshlrev_b32_e32 v0, 4, v18
	v_readlane_b32 s16, v254, 43
	s_add_u32 s2, s5, s1
	v_or3_b32 v2, v134, s6, v0
	v_mov_b32_e32 v3, v135
	v_readlane_b32 s17, v254, 44
	v_lshlrev_b32_e32 v0, 12, v136
	s_addc_u32 s3, 0, s3
	v_lshl_add_u64 v[20:21], s[16:17], 0, v[2:3]
	v_lshl_add_u64 v[2:3], s[2:3], 0, v[0:1]
	v_lshlrev_b32_e32 v0, 5, v18
	v_readlane_b32 s36, v253, 55
	v_lshl_add_u64 v[2:3], v[2:3], 0, v[0:1]
	v_readlane_b32 s50, v254, 5
	v_readlane_b32 s51, v254, 6
	s_mov_b64 s[2:3], 0
	v_readlane_b32 s37, v253, 56
	v_lshl_add_u64 v[22:23], s[50:51], 0, v[2:3]
	v_mov_b32_e32 v2, 0
	v_mov_b32_e32 v3, v2
	v_mov_b32_e32 v4, v2
	v_mov_b32_e32 v5, v2
	v_mov_b32_e32 v6, v2
	v_mov_b32_e32 v7, v2
	v_mov_b32_e32 v8, v2
	v_mov_b32_e32 v9, v2
	v_mov_b32_e32 v10, v2
	v_mov_b32_e32 v11, v2
	v_mov_b32_e32 v12, v2
	v_mov_b32_e32 v13, v2
	v_mov_b32_e32 v14, v2
	v_mov_b32_e32 v15, v2
	v_mov_b32_e32 v16, v2
	v_mov_b32_e32 v17, v2
	v_readlane_b32 s38, v253, 57
	v_readlane_b32 s39, v253, 58
	v_readlane_b32 s40, v253, 59
	v_readlane_b32 s41, v253, 60
	v_readlane_b32 s42, v253, 61
	v_readlane_b32 s43, v253, 62
	v_readlane_b32 s44, v253, 63
	v_readlane_b32 s45, v254, 0
	v_readlane_b32 s46, v254, 1
	v_readlane_b32 s47, v254, 2
	v_readlane_b32 s48, v254, 3
	v_readlane_b32 s49, v254, 4
	s_mov_b64 s[26:27], 0x8000
	v_lshl_add_u64 v[130:131], v[128:129], 0, s[26:27]
	v_lshl_add_u64 v[132:133], v[130:131], 0, s[26:27]
	v_lshl_add_u64 v[142:143], v[132:133], 0, s[26:27]
	global_load_dwordx4 v[24:27], v[128:129], off
	global_load_dwordx4 v[28:31], v[128:129], off offset:16
	v_lshl_add_u64 v[144:145], v[128:129], 0, s[72:73]
	global_load_dwordx4 v[32:35], v[144:145], off
	global_load_dwordx4 v[36:39], v[144:145], off offset:16
	v_lshl_add_u64 v[144:145], v[128:129], 0, s[74:75]
	global_load_dwordx4 v[40:43], v[144:145], off
	global_load_dwordx4 v[44:47], v[144:145], off offset:16
	v_lshl_add_u64 v[144:145], v[128:129], 0, s[76:77]
	global_load_dwordx4 v[48:51], v[144:145], off
	global_load_dwordx4 v[52:55], v[144:145], off offset:16
	global_load_dwordx4 v[56:59], v[130:131], off
	global_load_dwordx4 v[60:63], v[130:131], off offset:16
	v_lshl_add_u64 v[144:145], v[130:131], 0, s[72:73]
	global_load_dwordx4 v[64:67], v[144:145], off
	global_load_dwordx4 v[68:71], v[144:145], off offset:16
	v_lshl_add_u64 v[144:145], v[130:131], 0, s[74:75]
	global_load_dwordx4 v[72:75], v[144:145], off
	global_load_dwordx4 v[76:79], v[144:145], off offset:16
	v_lshl_add_u64 v[144:145], v[130:131], 0, s[76:77]
	global_load_dwordx4 v[80:83], v[144:145], off
	global_load_dwordx4 v[84:87], v[144:145], off offset:16
	global_load_dwordx4 v[88:91], v[132:133], off
	global_load_dwordx4 v[92:95], v[132:133], off offset:16
	v_lshl_add_u64 v[144:145], v[132:133], 0, s[72:73]
	global_load_dwordx4 v[96:99], v[144:145], off
	global_load_dwordx4 v[100:103], v[144:145], off offset:16
	v_lshl_add_u64 v[144:145], v[132:133], 0, s[74:75]
	global_load_dwordx4 v[104:107], v[144:145], off
	global_load_dwordx4 v[108:111], v[144:145], off offset:16
	v_lshl_add_u64 v[144:145], v[132:133], 0, s[76:77]
	global_load_dwordx4 v[112:115], v[144:145], off
	global_load_dwordx4 v[116:119], v[144:145], off offset:16
	global_load_dwordx4 v[120:123], v[142:143], off
	global_load_dwordx4 v[124:127], v[142:143], off offset:16
	s_waitcnt vmcnt(24)
	v_cvt_pk_bf16_f32 v24, v24, v25
	v_cvt_pk_bf16_f32 v25, v26, v27
	v_cvt_pk_bf16_f32 v26, v28, v29
	v_cvt_pk_bf16_f32 v27, v30, v31
	ds_write_b128 v138, v[24:27]
	v_lshl_add_u64 v[144:145], v[142:143], 0, s[72:73]
	global_load_dwordx4 v[24:27], v[144:145], off
	global_load_dwordx4 v[28:31], v[144:145], off offset:16
	s_waitcnt vmcnt(24)
	v_cvt_pk_bf16_f32 v32, v32, v33
	v_cvt_pk_bf16_f32 v33, v34, v35
	v_cvt_pk_bf16_f32 v34, v36, v37
	v_cvt_pk_bf16_f32 v35, v38, v39
	ds_write_b128 v138, v[32:35] offset:128
	v_lshl_add_u64 v[144:145], v[142:143], 0, s[74:75]
	global_load_dwordx4 v[32:35], v[144:145], off
	global_load_dwordx4 v[36:39], v[144:145], off offset:16
	s_waitcnt vmcnt(24)
; #define LAS __attribute__((address_space(3)))
; __device__ __forceinline__ bf16x8 load8f_bf(const float* p) { const f32x4 a = *(const f32x4*)p, b = *(const f32x4*)(p + 4); return pack8v(a, b); }
; __device__ __forceinline__ int voff_x(int key, int d) { return ((key >> 3) * 8 + (d >> 5)) * 512 + (key & 7) * 64 + (d & 31) * 2; }
; __device__ __forceinline__ void xattn_sample_unit(const Params& P, int l, int b, int h, LAS unsigned char* lds, int tid_) {
;     ...
; #pragma unroll 4
;     for (int i = 0; i < 16; ++i) { const int idx = lane + 64 * i, vr = idx >> 5, ch = idx & 31;
;         *(LAS bf16x8*)(wl + voff_x(vr, 8 * ch)) = load8f_bf(CV + (size_t)vr * 1024 + 8 * ch); }
;     f32x16 S;
; #pragma unroll
;     for (int e = 0; e < 16; ++e) S[e] = 0.f;
; #pragma unroll 4
;     for (int ks = 0; ks < 16; ++ks) {
;         const bf16x8 qf = *(const bf16x8*)(Q2 + (size_t)qrow * D + h * 256 + 16 * ks + 8 * hi);
;         const bf16x8 kf = load8f_bf(CK + (size_t)r * 1024 + 16 * ks + 8 * hi);
;         S = __builtin_amdgcn_mfma_f32_32x32x16_bf16(kf, qf, S, 0, 0, 0);
;     }
	v_cvt_pk_bf16_f32 v40, v40, v41
	v_cvt_pk_bf16_f32 v41, v42, v43
	v_cvt_pk_bf16_f32 v42, v44, v45
	v_cvt_pk_bf16_f32 v43, v46, v47
	ds_write_b128 v138, v[40:43] offset:256
	v_lshl_add_u64 v[144:145], v[142:143], 0, s[76:77]
	global_load_dwordx4 v[40:43], v[144:145], off
	global_load_dwordx4 v[44:47], v[144:145], off offset:16
	s_waitcnt vmcnt(24)
	v_cvt_pk_bf16_f32 v48, v48, v49
	v_cvt_pk_bf16_f32 v49, v50, v51
	v_cvt_pk_bf16_f32 v50, v52, v53
	v_cvt_pk_bf16_f32 v51, v54, v55
	ds_write_b128 v138, v[48:51] offset:384
	global_load_dwordx4 v[48:51], v[20:21], off offset:-64
	global_load_dwordx4 v[52:55], v[22:23], off
	s_waitcnt vmcnt(24)
	v_cvt_pk_bf16_f32 v56, v56, v57
	v_cvt_pk_bf16_f32 v57, v58, v59
	v_cvt_pk_bf16_f32 v58, v60, v61
	v_cvt_pk_bf16_f32 v59, v62, v63
	ds_write_b128 v138, v[56:59] offset:4096
	global_load_dwordx4 v[56:59], v[22:23], off offset:16
	global_load_dwordx4 v[60:63], v[20:21], off offset:-32
	s_waitcnt vmcnt(24)
	v_cvt_pk_bf16_f32 v64, v64, v65
	v_cvt_pk_bf16_f32 v65, v66, v67
	v_cvt_pk_bf16_f32 v66, v68, v69
	v_cvt_pk_bf16_f32 v67, v70, v71
	ds_write_b128 v138, v[64:67] offset:4224
	global_load_dwordx4 v[64:67], v[22:23], off offset:64
	global_load_dwordx4 v[68:71], v[22:23], off offset:80
	s_waitcnt vmcnt(24)
	v_cvt_pk_bf16_f32 v72, v72, v73
	v_cvt_pk_bf16_f32 v73, v74, v75
	v_cvt_pk_bf16_f32 v74, v76, v77
	v_cvt_pk_bf16_f32 v75, v78, v79
	ds_write_b128 v138, v[72:75] offset:4352
	global_load_dwordx4 v[72:75], v[20:21], off
	global_load_dwordx4 v[76:79], v[22:23], off offset:128
	s_waitcnt vmcnt(24)
	v_cvt_pk_bf16_f32 v80, v80, v81
	v_cvt_pk_bf16_f32 v81, v82, v83
	v_cvt_pk_bf16_f32 v82, v84, v85
	v_cvt_pk_bf16_f32 v83, v86, v87
	ds_write_b128 v138, v[80:83] offset:4480
	global_load_dwordx4 v[80:83], v[22:23], off offset:144
	global_load_dwordx4 v[84:87], v[20:21], off offset:32
	s_waitcnt vmcnt(24)
	v_cvt_pk_bf16_f32 v88, v88, v89
	v_cvt_pk_bf16_f32 v89, v90, v91
	v_cvt_pk_bf16_f32 v90, v92, v93
	v_cvt_pk_bf16_f32 v91, v94, v95
	ds_write_b128 v138, v[88:91] offset:8192
	global_load_dwordx4 v[88:91], v[22:23], off offset:192
	global_load_dwordx4 v[92:95], v[22:23], off offset:208
	s_waitcnt vmcnt(24)
	v_cvt_pk_bf16_f32 v96, v96, v97
	v_cvt_pk_bf16_f32 v97, v98, v99
	v_cvt_pk_bf16_f32 v98, v100, v101
	v_cvt_pk_bf16_f32 v99, v102, v103
	ds_write_b128 v138, v[96:99] offset:8320
	global_load_dwordx4 v[96:99], v[20:21], off offset:64
	global_load_dwordx4 v[100:103], v[22:23], off offset:256
	s_waitcnt vmcnt(24)
	v_cvt_pk_bf16_f32 v104, v104, v105
	v_cvt_pk_bf16_f32 v105, v106, v107
	v_cvt_pk_bf16_f32 v106, v108, v109
	v_cvt_pk_bf16_f32 v107, v110, v111
	ds_write_b128 v138, v[104:107] offset:8448
	global_load_dwordx4 v[104:107], v[22:23], off offset:272
	global_load_dwordx4 v[108:111], v[20:21], off offset:96
	s_waitcnt vmcnt(24)
	v_cvt_pk_bf16_f32 v112, v112, v113
	v_cvt_pk_bf16_f32 v113, v114, v115
	v_cvt_pk_bf16_f32 v114, v116, v117
	v_cvt_pk_bf16_f32 v115, v118, v119
	ds_write_b128 v138, v[112:115] offset:8576
	global_load_dwordx4 v[112:115], v[22:23], off offset:320
	global_load_dwordx4 v[116:119], v[22:23], off offset:336
	s_waitcnt vmcnt(24)
	v_cvt_pk_bf16_f32 v120, v120, v121
	v_cvt_pk_bf16_f32 v121, v122, v123
	v_cvt_pk_bf16_f32 v122, v124, v125
	v_cvt_pk_bf16_f32 v123, v126, v127
	ds_write_b128 v138, v[120:123] offset:12288
	global_load_dwordx4 v[120:123], v[20:21], off offset:128
	global_load_dwordx4 v[124:127], v[22:23], off offset:384
	s_waitcnt vmcnt(24)
	v_cvt_pk_bf16_f32 v24, v24, v25
	v_cvt_pk_bf16_f32 v25, v26, v27
	v_cvt_pk_bf16_f32 v26, v28, v29
	v_cvt_pk_bf16_f32 v27, v30, v31
	ds_write_b128 v138, v[24:27] offset:12416
	global_load_dwordx4 v[24:27], v[22:23], off offset:400
	global_load_dwordx4 v[28:31], v[20:21], off offset:160
	s_waitcnt vmcnt(24)
	v_cvt_pk_bf16_f32 v32, v32, v33
	v_cvt_pk_bf16_f32 v33, v34, v35
	v_cvt_pk_bf16_f32 v34, v36, v37
	v_cvt_pk_bf16_f32 v35, v38, v39
	ds_write_b128 v138, v[32:35] offset:12544
	global_load_dwordx4 v[32:35], v[22:23], off offset:448
	global_load_dwordx4 v[36:39], v[22:23], off offset:464
	s_waitcnt vmcnt(24)
	v_cvt_pk_bf16_f32 v40, v40, v41
	v_cvt_pk_bf16_f32 v41, v42, v43
	v_cvt_pk_bf16_f32 v42, v44, v45
	v_cvt_pk_bf16_f32 v43, v46, v47
	ds_write_b128 v138, v[40:43] offset:12672
	global_load_dwordx4 v[40:43], v[20:21], off offset:192
	global_load_dwordx4 v[44:47], v[22:23], off offset:512
	s_waitcnt vmcnt(23)
	v_cvt_pk_bf16_f32 v52, v52, v53
	v_cvt_pk_bf16_f32 v53, v54, v55
	v_cvt_pk_bf16_f32 v54, v56, v57
	v_cvt_pk_bf16_f32 v55, v58, v59
	s_nop 1
	v_mfma_f32_32x32x16_bf16 v[2:17], v[52:55], v[48:51], v[2:17]
	global_load_dwordx4 v[48:51], v[22:23], off offset:528
	global_load_dwordx4 v[52:55], v[20:21], off offset:224
	global_load_dwordx4 v[56:59], v[22:23], off offset:576
	s_waitcnt vmcnt(23)
	v_cvt_pk_bf16_f32 v64, v64, v65
	v_cvt_pk_bf16_f32 v65, v66, v67
	v_cvt_pk_bf16_f32 v66, v68, v69
	v_cvt_pk_bf16_f32 v67, v70, v71
	s_nop 1
	v_mfma_f32_32x32x16_bf16 v[2:17], v[64:67], v[60:63], v[2:17]
	global_load_dwordx4 v[60:63], v[22:23], off offset:592
	global_load_dwordx4 v[64:67], v[20:21], off offset:256
	global_load_dwordx4 v[68:71], v[22:23], off offset:640
	s_waitcnt vmcnt(23)
	v_cvt_pk_bf16_f32 v76, v76, v77
	v_cvt_pk_bf16_f32 v77, v78, v79
	v_cvt_pk_bf16_f32 v78, v80, v81
	v_cvt_pk_bf16_f32 v79, v82, v83
	s_nop 1
	v_mfma_f32_32x32x16_bf16 v[2:17], v[76:79], v[72:75], v[2:17]
	global_load_dwordx4 v[72:75], v[22:23], off offset:656
	global_load_dwordx4 v[76:79], v[20:21], off offset:288
	global_load_dwordx4 v[80:83], v[22:23], off offset:704
	s_waitcnt vmcnt(23)
; __device__ __forceinline__ bf16x8 load8f_bf(const float* p) { const f32x4 a = *(const f32x4*)p, b = *(const f32x4*)(p + 4); return pack8v(a, b); }
; __device__ __forceinline__ void xattn_sample_unit(const Params& P, int l, int b, int h, LAS unsigned char* lds, int tid_) {
;     ...
; #pragma unroll 4
;     for (int ks = 0; ks < 16; ++ks) {
;         const bf16x8 qf = *(const bf16x8*)(Q2 + (size_t)qrow * D + h * 256 + 16 * ks + 8 * hi);
;         const bf16x8 kf = load8f_bf(CK + (size_t)r * 1024 + 16 * ks + 8 * hi);
;         S = __builtin_amdgcn_mfma_f32_32x32x16_bf16(kf, qf, S, 0, 0, 0);
;     }
;     float mx = S[0];
; #pragma unroll
;     for (int e = 1; e < 16; ++e) mx = fmaxf(mx, S[e]);
;     mx = fmaxf(mx, __shfl_xor(mx, 32));
;     float ls = 0.f;
; #pragma unroll
;     for (int e = 0; e < 16; ++e) { S[e] = __builtin_amdgcn_exp2f(S[e] - mx); ls += S[e]; }
;     ls += __shfl_xor(ls, 32);
	v_cvt_pk_bf16_f32 v88, v88, v89
	v_cvt_pk_bf16_f32 v89, v90, v91
	v_cvt_pk_bf16_f32 v90, v92, v93
	v_cvt_pk_bf16_f32 v91, v94, v95
	s_nop 1
	v_mfma_f32_32x32x16_bf16 v[2:17], v[88:91], v[84:87], v[2:17]
	global_load_dwordx4 v[84:87], v[22:23], off offset:720
	global_load_dwordx4 v[88:91], v[20:21], off offset:320
	global_load_dwordx4 v[92:95], v[22:23], off offset:768
	s_waitcnt vmcnt(23)
	v_cvt_pk_bf16_f32 v100, v100, v101
	v_cvt_pk_bf16_f32 v101, v102, v103
	v_cvt_pk_bf16_f32 v102, v104, v105
	v_cvt_pk_bf16_f32 v103, v106, v107
	s_nop 1
	v_mfma_f32_32x32x16_bf16 v[2:17], v[100:103], v[96:99], v[2:17]
	global_load_dwordx4 v[96:99], v[22:23], off offset:784
	global_load_dwordx4 v[100:103], v[20:21], off offset:352
	global_load_dwordx4 v[104:107], v[22:23], off offset:832
	s_waitcnt vmcnt(23)
	v_cvt_pk_bf16_f32 v112, v112, v113
	v_cvt_pk_bf16_f32 v113, v114, v115
	v_cvt_pk_bf16_f32 v114, v116, v117
	v_cvt_pk_bf16_f32 v115, v118, v119
	s_nop 1
	v_mfma_f32_32x32x16_bf16 v[2:17], v[112:115], v[108:111], v[2:17]
	global_load_dwordx4 v[108:111], v[22:23], off offset:848
	global_load_dwordx4 v[112:115], v[20:21], off offset:384
	global_load_dwordx4 v[116:119], v[22:23], off offset:896
	s_waitcnt vmcnt(23)
	v_cvt_pk_bf16_f32 v124, v124, v125
	v_cvt_pk_bf16_f32 v125, v126, v127
	v_cvt_pk_bf16_f32 v126, v24, v25
	v_cvt_pk_bf16_f32 v127, v26, v27
	s_nop 1
	v_mfma_f32_32x32x16_bf16 v[2:17], v[124:127], v[120:123], v[2:17]
	global_load_dwordx4 v[120:123], v[22:23], off offset:912
	global_load_dwordx4 v[124:127], v[20:21], off offset:416
	global_load_dwordx4 v[24:27], v[22:23], off offset:960
	s_waitcnt vmcnt(23)
	v_cvt_pk_bf16_f32 v32, v32, v33
	v_cvt_pk_bf16_f32 v33, v34, v35
	v_cvt_pk_bf16_f32 v34, v36, v37
	v_cvt_pk_bf16_f32 v35, v38, v39
	s_nop 1
	v_mfma_f32_32x32x16_bf16 v[2:17], v[32:35], v[28:31], v[2:17]
	global_load_dwordx4 v[28:31], v[22:23], off offset:976
	s_waitcnt vmcnt(21)
	v_cvt_pk_bf16_f32 v44, v44, v45
	v_cvt_pk_bf16_f32 v45, v46, v47
	v_cvt_pk_bf16_f32 v46, v48, v49
	v_cvt_pk_bf16_f32 v47, v50, v51
	s_nop 1
	v_mfma_f32_32x32x16_bf16 v[2:17], v[44:47], v[40:43], v[2:17]
	s_waitcnt vmcnt(18)
	v_cvt_pk_bf16_f32 v56, v56, v57
	v_cvt_pk_bf16_f32 v57, v58, v59
	v_cvt_pk_bf16_f32 v58, v60, v61
	v_cvt_pk_bf16_f32 v59, v62, v63
	s_nop 1
	v_mfma_f32_32x32x16_bf16 v[2:17], v[56:59], v[52:55], v[2:17]
	s_waitcnt vmcnt(15)
	v_cvt_pk_bf16_f32 v68, v68, v69
	v_cvt_pk_bf16_f32 v69, v70, v71
	v_cvt_pk_bf16_f32 v70, v72, v73
	v_cvt_pk_bf16_f32 v71, v74, v75
	s_nop 1
	v_mfma_f32_32x32x16_bf16 v[2:17], v[68:71], v[64:67], v[2:17]
	s_waitcnt vmcnt(12)
	v_cvt_pk_bf16_f32 v80, v80, v81
	v_cvt_pk_bf16_f32 v81, v82, v83
	v_cvt_pk_bf16_f32 v82, v84, v85
	v_cvt_pk_bf16_f32 v83, v86, v87
	s_nop 1
	v_mfma_f32_32x32x16_bf16 v[2:17], v[80:83], v[76:79], v[2:17]
	s_waitcnt vmcnt(9)
	v_cvt_pk_bf16_f32 v92, v92, v93
	v_cvt_pk_bf16_f32 v93, v94, v95
	v_cvt_pk_bf16_f32 v94, v96, v97
	v_cvt_pk_bf16_f32 v95, v98, v99
	s_nop 1
	v_mfma_f32_32x32x16_bf16 v[2:17], v[92:95], v[88:91], v[2:17]
	s_waitcnt vmcnt(6)
	v_cvt_pk_bf16_f32 v104, v104, v105
	v_cvt_pk_bf16_f32 v105, v106, v107
	v_cvt_pk_bf16_f32 v106, v108, v109
	v_cvt_pk_bf16_f32 v107, v110, v111
	s_nop 1
	v_mfma_f32_32x32x16_bf16 v[2:17], v[104:107], v[100:103], v[2:17]
	s_waitcnt vmcnt(3)
	v_cvt_pk_bf16_f32 v116, v116, v117
	v_cvt_pk_bf16_f32 v117, v118, v119
	v_cvt_pk_bf16_f32 v118, v120, v121
	v_cvt_pk_bf16_f32 v119, v122, v123
	s_nop 1
	v_mfma_f32_32x32x16_bf16 v[2:17], v[116:119], v[112:115], v[2:17]
	s_waitcnt vmcnt(0)
	v_cvt_pk_bf16_f32 v24, v24, v25
	v_cvt_pk_bf16_f32 v25, v26, v27
	v_cvt_pk_bf16_f32 v26, v28, v29
	v_cvt_pk_bf16_f32 v27, v30, v31
	s_nop 1
	v_mfma_f32_32x32x16_bf16 v[2:17], v[24:27], v[124:127], v[2:17]
	s_nop 1
	s_nop 10
	v_max_f32_e32 v0, v3, v3
	v_max_f32_e32 v20, v2, v2
	v_max_f32_e32 v0, v20, v0
	v_max3_f32 v0, v0, v4, v5
	v_max3_f32 v0, v0, v6, v7
	v_max3_f32 v0, v0, v8, v9
	v_and_b32_e32 v21, 64, v210
	v_max3_f32 v0, v0, v10, v11
	v_xor_b32_e32 v20, 32, v210
	v_add_u32_e32 v21, 64, v21
	v_max3_f32 v0, v0, v12, v13
	v_cmp_lt_i32_e32 vcc, v20, v21
	v_max3_f32 v0, v0, v14, v15
	v_max3_f32 v0, v0, v16, v17
	v_cndmask_b32_e32 v20, v210, v20, vcc
	v_lshlrev_b32_e32 v20, 2, v20
	ds_bpermute_b32 v21, v20, v0
	s_add_i32 s4, s4, 0
	v_lshlrev_b32_e32 v142, 8, v18
	v_cmp_gt_u32_e32 vcc, 16, v139
	s_waitcnt lgkmcnt(0)
; __device__ __forceinline__ unsigned cvt_pk_bf16(float lo, float hi) { unsigned r; asm("v_cvt_pk_bf16_f32 %0, %1, %2" : "=v"(r) : "v"(lo), "v"(hi)); return r; }
; __device__ __forceinline__ int voff_x(int key, int d) { return ((key >> 3) * 8 + (d >> 5)) * 512 + (key & 7) * 64 + (d & 31) * 2; }
; __device__ __forceinline__ void xattn_sample_unit(const Params& P, int l, int b, int h, LAS unsigned char* lds, int tid_) {
;     ...
;     float mx = S[0];
; #pragma unroll
;     for (int e = 1; e < 16; ++e) mx = fmaxf(mx, S[e]);
;     mx = fmaxf(mx, __shfl_xor(mx, 32));
;     float ls = 0.f;
; #pragma unroll
;     for (int e = 0; e < 16; ++e) { S[e] = __builtin_amdgcn_exp2f(S[e] - mx); ls += S[e]; }
;     ls += __shfl_xor(ls, 32);
;     bf16x8 pf[2];
; #pragma unroll
;     for (int s2 = 0; s2 < 2; ++s2) { u32x4 w; w.x = cvt_pk_bf16(S[8 * s2 + 0], S[8 * s2 + 1]); w.y = cvt_pk_bf16(S[8 * s2 + 2], S[8 * s2 + 3]); w.z = cvt_pk_bf16(S[8 * s2 + 4], S[8 * s2 + 5]); w.w = cvt_pk_bf16(S[8 * s2 + 6], S[8 * s2 + 7]);
;         pf[s2] = __builtin_bit_cast(bf16x8, w); }
;     f32x16 O[8];
;     const int trow = 4 * hi + ((lane & 15) >> 2), tcol = 16 * ((lane >> 4) & 1) + 4 * (lane & 3);
; #pragma unroll
;     for (int db = 0; db < 8; ++db) {
; #pragma unroll
;         for (int e = 0; e < 16; ++e) O[db][e] = 0.f;
; #pragma unroll
;         for (int s2 = 0; s2 < 2; ++s2) {
;             const s16x4 a0 = tr_read(wl + voff_x(16 * s2 + trow, 32 * db + tcol));
;             const s16x4 a1 = tr_read(wl + voff_x(16 * s2 + 8 + trow, 32 * db + tcol));
;             const bf16x8 vf = (bf16x8){a0[0], a0[1], a0[2], a0[3], a1[0], a1[1], a1[2], a1[3]};
;             O[db] = __builtin_amdgcn_mfma_f32_32x32x16_bf16(vf, pf[s2], O[db], 0, 0, 0);
;         }
;     }
;     if (lane < 16) { ml[(wave * 16 + lane) * 2] = mx; ml[(wave * 16 + lane) * 2 + 1] = ls; }
	v_max_f32_e32 v21, v21, v21
	v_max_f32_e32 v138, v0, v21
	v_sub_f32_e32 v0, v2, v138
	v_exp_f32_e32 v2, v0
	v_sub_f32_e32 v3, v3, v138
	v_exp_f32_e32 v3, v3
	v_sub_f32_e32 v4, v4, v138
	v_exp_f32_e32 v4, v4
	v_sub_f32_e32 v5, v5, v138
	v_exp_f32_e32 v5, v5
	v_sub_f32_e32 v6, v6, v138
	v_add_f32_e32 v0, 0, v2
	v_exp_f32_e32 v6, v6
	v_sub_f32_e32 v7, v7, v138
	v_add_f32_e32 v0, v3, v0
	v_exp_f32_e32 v7, v7
	v_sub_f32_e32 v8, v8, v138
	v_add_f32_e32 v0, v4, v0
	v_exp_f32_e32 v8, v8
	v_sub_f32_e32 v9, v9, v138
	v_add_f32_e32 v0, v5, v0
	v_exp_f32_e32 v9, v9
	v_sub_f32_e32 v10, v10, v138
	v_add_f32_e32 v0, v6, v0
	v_exp_f32_e32 v10, v10
	v_sub_f32_e32 v11, v11, v138
	v_add_f32_e32 v0, v7, v0
	v_exp_f32_e32 v11, v11
	v_sub_f32_e32 v12, v12, v138
	v_add_f32_e32 v0, v8, v0
	v_exp_f32_e32 v12, v12
	v_sub_f32_e32 v13, v13, v138
	v_cvt_pk_bf16_f32 v114, v2, v3
	v_and_b32_e32 v2, 16, v137
	v_lshlrev_b32_e32 v3, 2, v137
	v_add_f32_e32 v0, v9, v0
	v_exp_f32_e32 v13, v13
	v_sub_f32_e32 v14, v14, v138
	v_and_or_b32 v2, v3, 12, v2
	v_add_f32_e32 v0, v10, v0
	v_exp_f32_e32 v14, v14
	v_sub_f32_e32 v15, v15, v138
	v_cvt_pk_bf16_f32 v115, v4, v5
	v_and_b32_e32 v3, 0xc0, v19
	v_lshlrev_b32_e32 v2, 1, v2
	v_add_u32_e32 v4, s4, v142
	v_add_f32_e32 v0, v11, v0
	v_exp_f32_e32 v15, v15
	v_sub_f32_e32 v16, v16, v138
	v_add3_u32 v143, v4, v3, v2
	v_add_f32_e32 v0, v12, v0
	v_exp_f32_e32 v16, v16
	v_sub_f32_e32 v17, v17, v138
	ds_read_b64_tr_b16 v[2:3], v143
	ds_read_b64_tr_b16 v[4:5], v143 offset:4096
	v_add_f32_e32 v0, v13, v0
	v_exp_f32_e32 v17, v17
	v_add_f32_e32 v0, v14, v0
	v_add_f32_e32 v0, v15, v0
	v_add_f32_e32 v0, v16, v0
	v_add_f32_e32 v0, v17, v0
	v_cvt_pk_bf16_f32 v116, v6, v7
	v_cvt_pk_bf16_f32 v117, v8, v9
	v_cvt_pk_bf16_f32 v130, v10, v11
	v_cvt_pk_bf16_f32 v131, v12, v13
	v_cvt_pk_bf16_f32 v132, v14, v15
	v_cvt_pk_bf16_f32 v133, v16, v17
	ds_bpermute_b32 v141, v20, v0
	s_waitcnt lgkmcnt(1)
	v_mfma_f32_32x32x16_bf16 v[2:17], v[2:5], v[114:117], 0
	ds_read_b64_tr_b16 v[18:19], v143 offset:8192
	ds_read_b64_tr_b16 v[20:21], v143 offset:12288
	s_waitcnt lgkmcnt(0)
	v_mfma_f32_32x32x16_bf16 v[2:17], v[18:21], v[130:133], v[2:17]
	ds_read_b64_tr_b16 v[18:19], v143 offset:512
	ds_read_b64_tr_b16 v[20:21], v143 offset:4608
	ds_read_b64_tr_b16 v[34:35], v143 offset:8704
	ds_read_b64_tr_b16 v[36:37], v143 offset:12800
	s_waitcnt lgkmcnt(2)
	v_mfma_f32_32x32x16_bf16 v[18:33], v[18:21], v[114:117], 0
	s_waitcnt lgkmcnt(0)
	v_mfma_f32_32x32x16_bf16 v[18:33], v[34:37], v[130:133], v[18:33]
	ds_read_b64_tr_b16 v[34:35], v143 offset:1024
	ds_read_b64_tr_b16 v[36:37], v143 offset:5120
	ds_read_b64_tr_b16 v[50:51], v143 offset:9216
	ds_read_b64_tr_b16 v[52:53], v143 offset:13312
	s_waitcnt lgkmcnt(2)
	v_mfma_f32_32x32x16_bf16 v[34:49], v[34:37], v[114:117], 0
	s_waitcnt lgkmcnt(0)
	v_mfma_f32_32x32x16_bf16 v[34:49], v[50:53], v[130:133], v[34:49]
	ds_read_b64_tr_b16 v[50:51], v143 offset:1536
	ds_read_b64_tr_b16 v[52:53], v143 offset:5632
	ds_read_b64_tr_b16 v[66:67], v143 offset:9728
	ds_read_b64_tr_b16 v[68:69], v143 offset:13824
	s_waitcnt lgkmcnt(2)
	v_mfma_f32_32x32x16_bf16 v[50:65], v[50:53], v[114:117], 0
	s_waitcnt lgkmcnt(0)
	v_mfma_f32_32x32x16_bf16 v[50:65], v[66:69], v[130:133], v[50:65]
	ds_read_b64_tr_b16 v[66:67], v143 offset:2048
	ds_read_b64_tr_b16 v[68:69], v143 offset:6144
	ds_read_b64_tr_b16 v[82:83], v143 offset:10240
	ds_read_b64_tr_b16 v[84:85], v143 offset:14336
	s_waitcnt lgkmcnt(2)
	v_mfma_f32_32x32x16_bf16 v[66:81], v[66:69], v[114:117], 0
	s_waitcnt lgkmcnt(0)
	v_mfma_f32_32x32x16_bf16 v[66:81], v[82:85], v[130:133], v[66:81]
	ds_read_b64_tr_b16 v[82:83], v143 offset:2560
	ds_read_b64_tr_b16 v[84:85], v143 offset:6656
	ds_read_b64_tr_b16 v[98:99], v143 offset:10752
	ds_read_b64_tr_b16 v[100:101], v143 offset:14848
	s_waitcnt lgkmcnt(2)
	v_mfma_f32_32x32x16_bf16 v[82:97], v[82:85], v[114:117], 0
	s_waitcnt lgkmcnt(0)
	v_mfma_f32_32x32x16_bf16 v[82:97], v[98:101], v[130:133], v[82:97]
	ds_read_b64_tr_b16 v[98:99], v143 offset:3072
	ds_read_b64_tr_b16 v[100:101], v143 offset:7168
	ds_read_b64_tr_b16 v[118:119], v143 offset:11264
	ds_read_b64_tr_b16 v[120:121], v143 offset:15360
	s_waitcnt lgkmcnt(2)
	v_mfma_f32_32x32x16_bf16 v[98:113], v[98:101], v[114:117], 0
	s_waitcnt lgkmcnt(0)
	v_mfma_f32_32x32x16_bf16 v[98:113], v[118:121], v[130:133], v[98:113]
	ds_read_b64_tr_b16 v[118:119], v143 offset:3584
	ds_read_b64_tr_b16 v[120:121], v143 offset:7680
	ds_read_b64_tr_b16 v[144:145], v143 offset:11776
	ds_read_b64_tr_b16 v[146:147], v143 offset:15872
	s_waitcnt lgkmcnt(2)
	v_mfma_f32_32x32x16_bf16 v[114:129], v[118:121], v[114:117], 0
	s_waitcnt lgkmcnt(0)
	v_mfma_f32_32x32x16_bf16 v[114:129], v[144:147], v[130:133], v[114:129]
	s_and_saveexec_b64 s[2:3], vcc
	s_mov_b32 s45, s18
	s_mov_b32 s47, s19
	s_movk_i32 s48, 0xc0
	s_mov_b32 s39, 0x20000
	s_mov_b32 s40, 0x28000
	s_mov_b32 s41, 0x30000
	s_mov_b32 s42, 0x38000
	s_mov_b32 s43, 0x60000
	s_cbranch_execz .LBB0_594
	s_lshl_b32 s0, s0, 2
	s_add_i32 s0, s0, 0
	v_lshl_add_u32 v130, v139, 3, s0
	v_add_u32_e32 v130, 0x20000, v130
	v_add_f32_e32 v139, v0, v141
	ds_write_b64 v130, v[138:139]

; __device__ __forceinline__ void small_gemm_res(LAS unsigned char* lds, const bf16_t* A, const bf16_t* Bt, int K, int unit, bf16_t* XB, float* SS, float sc) {
;     ...
;     const bf16_t* ap = A + (size_t)(row0 + li) * K + 8 * g4 + 32 * wave * KS;
;     const bf16_t* bp = Bt + (size_t)(col0 + li) * K + 8 * g4 + 32 * wave * KS;
; #pragma unroll 6
;     for (int ks = 0; ks < KS; ++ks) {
;         const bf16x8 a0 = *(const bf16x8*)(ap + 32 * ks), a1 = *(const bf16x8*)(ap + (size_t)16 * K + 32 * ks);
; #pragma unroll
;         for (int t = 0; t < 4; ++t) { const bf16x8 b = *(const bf16x8*)(bp + (size_t)16 * t * K + 32 * ks);
;             acc[0][t] = __builtin_amdgcn_mfma_f32_16x16x32_bf16(b, a0, acc[0][t], 0, 0, 0); acc[1][t] = __builtin_amdgcn_mfma_f32_16x16x32_bf16(b, a1, acc[1][t], 0, 0, 0); }
;     }
.Lsgr_k11:
	v_bfe_u32 v62, v208, 2, 4
	v_and_b32_e32 v63, 3, v208
	v_sub_u32_e32 v62, v62, v58
	v_mul_lo_u32 v62, v62, s7
	v_lshlrev_b32_e32 v63, 4, v63
	v_sub_u32_e32 v63, v63, v40
	v_lshl_add_u32 v62, v62, 1, v63
	v_ashrrev_i32_e32 v63, 31, v62
	v_lshl_add_u64 v[52:53], v[52:53], 0, s[28:29]
	v_lshl_add_u64 v[52:53], v[52:53], 0, v[62:63]
	v_lshl_add_u64 v[50:51], v[50:51], 0, s[28:29]
	v_lshl_add_u64 v[50:51], v[50:51], 0, v[62:63]
	v_lshl_add_u64 v[42:43], v[42:43], 0, s[28:29]
	v_lshl_add_u64 v[42:43], v[42:43], 0, v[62:63]
	v_lshl_add_u64 v[48:49], v[48:49], 0, s[28:29]
	v_lshl_add_u64 v[48:49], v[48:49], 0, v[62:63]
	v_lshl_add_u64 v[46:47], v[46:47], 0, s[28:29]
	v_lshl_add_u64 v[46:47], v[46:47], 0, v[62:63]
	v_lshl_add_u64 v[44:45], v[44:45], 0, s[28:29]
	v_lshl_add_u64 v[44:45], v[44:45], 0, v[62:63]
	s_lshl_b32 s34, s31, 8
	v_lshl_add_u32 v64, v58, 6, v40
	v_add_u32_e32 v64, s34, v64
	v_add_u32_e32 v65, 0x10000, v64
	s_add_i32 m0, s34, 0x0
	s_nop 0
	global_load_lds_dwordx4 v[52:53], off
	v_lshl_add_u64 v[52:53], v[52:53], 0, 64
	s_add_i32 m0, s34, 0x400
	s_nop 0
	global_load_lds_dwordx4 v[50:51], off
	v_lshl_add_u64 v[50:51], v[50:51], 0, 64
	s_add_i32 m0, s34, 0x800
	s_nop 0
	global_load_lds_dwordx4 v[42:43], off
	v_lshl_add_u64 v[42:43], v[42:43], 0, 64
	s_add_i32 m0, s34, 0xc00
	s_nop 0
	global_load_lds_dwordx4 v[48:49], off
	v_lshl_add_u64 v[48:49], v[48:49], 0, 64
	s_add_i32 m0, s34, 0x1000
	s_nop 0
	global_load_lds_dwordx4 v[46:47], off
	v_lshl_add_u64 v[46:47], v[46:47], 0, 64
	s_add_i32 m0, s34, 0x1400
	s_nop 0
	global_load_lds_dwordx4 v[44:45], off
	v_lshl_add_u64 v[44:45], v[44:45], 0, 64
	s_add_i32 m0, s34, 0x1800
	s_nop 0
	global_load_lds_dwordx4 v[52:53], off
	v_lshl_add_u64 v[52:53], v[52:53], 0, 64
	s_add_i32 m0, s34, 0x1c00
	s_nop 0
	global_load_lds_dwordx4 v[50:51], off
	v_lshl_add_u64 v[50:51], v[50:51], 0, 64
	s_add_i32 m0, s34, 0x10000
	s_nop 0
	global_load_lds_dwordx4 v[42:43], off
	v_lshl_add_u64 v[42:43], v[42:43], 0, 64
	s_add_i32 m0, s34, 0x10400
	s_nop 0
	global_load_lds_dwordx4 v[48:49], off
	v_lshl_add_u64 v[48:49], v[48:49], 0, 64
	s_add_i32 m0, s34, 0x10800
	s_nop 0
	global_load_lds_dwordx4 v[46:47], off
	v_lshl_add_u64 v[46:47], v[46:47], 0, 64
	s_add_i32 m0, s34, 0x10c00
	s_nop 0
	global_load_lds_dwordx4 v[44:45], off
	v_lshl_add_u64 v[44:45], v[44:45], 0, 64
	s_add_i32 m0, s34, 0x11000
	s_nop 0
	global_load_lds_dwordx4 v[52:53], off
	v_lshl_add_u64 v[52:53], v[52:53], 0, 64
	s_add_i32 m0, s34, 0x11400
	s_nop 0
	global_load_lds_dwordx4 v[50:51], off
	v_lshl_add_u64 v[50:51], v[50:51], 0, 64
	s_add_i32 m0, s34, 0x11800
	s_nop 0
	global_load_lds_dwordx4 v[42:43], off
	v_lshl_add_u64 v[42:43], v[42:43], 0, 64
	s_add_i32 m0, s34, 0x11c00
	s_nop 0
	global_load_lds_dwordx4 v[48:49], off
	v_lshl_add_u64 v[48:49], v[48:49], 0, 64
	s_waitcnt vmcnt(10)
	ds_read_b128 v[66:69], v64 offset:0
	ds_read_b128 v[70:73], v64 offset:1024
	ds_read_b128 v[74:77], v64 offset:2048
	ds_read_b128 v[78:81], v64 offset:3072
	ds_read_b128 v[82:85], v64 offset:4096
	ds_read_b128 v[86:89], v64 offset:5120
	s_waitcnt vmcnt(4)
	ds_read_b128 v[90:93], v64 offset:6144
	ds_read_b128 v[94:97], v64 offset:7168
	ds_read_b128 v[98:101], v65 offset:0
	ds_read_b128 v[102:105], v65 offset:1024
	ds_read_b128 v[106:109], v65 offset:2048
	ds_read_b128 v[110:113], v65 offset:3072
	s_waitcnt lgkmcnt(6)
	v_mfma_f32_16x16x32_bf16 v[30:33], v[74:77], v[66:69], v[30:33]
	v_mfma_f32_16x16x32_bf16 v[14:17], v[74:77], v[70:73], v[14:17]
	v_mfma_f32_16x16x32_bf16 v[26:29], v[78:81], v[66:69], v[26:29]
	v_mfma_f32_16x16x32_bf16 v[10:13], v[78:81], v[70:73], v[10:13]
	v_mfma_f32_16x16x32_bf16 v[22:25], v[82:85], v[66:69], v[22:25]
	v_mfma_f32_16x16x32_bf16 v[6:9], v[82:85], v[70:73], v[6:9]
	v_mfma_f32_16x16x32_bf16 v[18:21], v[86:89], v[66:69], v[18:21]
	v_mfma_f32_16x16x32_bf16 v[2:5], v[86:89], v[70:73], v[2:5]
	s_add_i32 m0, s34, 0x0
	s_nop 0
	global_load_lds_dwordx4 v[46:47], off
	v_lshl_add_u64 v[46:47], v[46:47], 0, 64
	s_add_i32 m0, s34, 0x400
	s_nop 0
	global_load_lds_dwordx4 v[44:45], off
	v_lshl_add_u64 v[44:45], v[44:45], 0, 64
	s_add_i32 m0, s34, 0x800
	s_nop 0
	global_load_lds_dwordx4 v[52:53], off
	v_lshl_add_u64 v[52:53], v[52:53], 0, 64
	s_add_i32 m0, s34, 0xc00
	s_nop 0
	global_load_lds_dwordx4 v[50:51], off
	v_lshl_add_u64 v[50:51], v[50:51], 0, 64
	s_add_i32 m0, s34, 0x1000
	s_nop 0
	global_load_lds_dwordx4 v[42:43], off
	v_lshl_add_u64 v[42:43], v[42:43], 0, 64
	s_add_i32 m0, s34, 0x1400
	s_nop 0
	global_load_lds_dwordx4 v[48:49], off
	v_lshl_add_u64 v[48:49], v[48:49], 0, 64
	s_waitcnt vmcnt(4)
	ds_read_b128 v[66:69], v65 offset:4096
	ds_read_b128 v[70:73], v65 offset:5120
	ds_read_b128 v[74:77], v65 offset:6144
	ds_read_b128 v[78:81], v65 offset:7168
	ds_read_b128 v[82:85], v64 offset:0
	ds_read_b128 v[86:89], v64 offset:1024
	s_waitcnt lgkmcnt(6)
	v_mfma_f32_16x16x32_bf16 v[30:33], v[98:101], v[90:93], v[30:33]
	v_mfma_f32_16x16x32_bf16 v[14:17], v[98:101], v[94:97], v[14:17]
	v_mfma_f32_16x16x32_bf16 v[26:29], v[102:105], v[90:93], v[26:29]
	v_mfma_f32_16x16x32_bf16 v[10:13], v[102:105], v[94:97], v[10:13]
	v_mfma_f32_16x16x32_bf16 v[22:25], v[106:109], v[90:93], v[22:25]
	v_mfma_f32_16x16x32_bf16 v[6:9], v[106:109], v[94:97], v[6:9]
	v_mfma_f32_16x16x32_bf16 v[18:21], v[110:113], v[90:93], v[18:21]
	v_mfma_f32_16x16x32_bf16 v[2:5], v[110:113], v[94:97], v[2:5]
	s_add_i32 m0, s34, 0x1800
	s_nop 0
	global_load_lds_dwordx4 v[46:47], off
	v_lshl_add_u64 v[46:47], v[46:47], 0, 64
	s_add_i32 m0, s34, 0x1c00
	s_nop 0
	global_load_lds_dwordx4 v[44:45], off
	v_lshl_add_u64 v[44:45], v[44:45], 0, 64
	s_add_i32 m0, s34, 0x10000
	s_nop 0
	global_load_lds_dwordx4 v[52:53], off
	v_lshl_add_u64 v[52:53], v[52:53], 0, 64
	s_add_i32 m0, s34, 0x10400
	s_nop 0
	global_load_lds_dwordx4 v[50:51], off
	v_lshl_add_u64 v[50:51], v[50:51], 0, 64
	s_add_i32 m0, s34, 0x10800
	s_nop 0
	global_load_lds_dwordx4 v[42:43], off
	v_lshl_add_u64 v[42:43], v[42:43], 0, 64
	s_add_i32 m0, s34, 0x10c00
	s_nop 0
	global_load_lds_dwordx4 v[48:49], off
	v_lshl_add_u64 v[48:49], v[48:49], 0, 64
	s_waitcnt vmcnt(4)
; __device__ __forceinline__ void small_gemm_res(LAS unsigned char* lds, const bf16_t* A, const bf16_t* Bt, int K, int unit, bf16_t* XB, float* SS, float sc) {
;     ...
;     const bf16_t* ap = A + (size_t)(row0 + li) * K + 8 * g4 + 32 * wave * KS;
;     const bf16_t* bp = Bt + (size_t)(col0 + li) * K + 8 * g4 + 32 * wave * KS;
; #pragma unroll 6
;     for (int ks = 0; ks < KS; ++ks) {
;         const bf16x8 a0 = *(const bf16x8*)(ap + 32 * ks), a1 = *(const bf16x8*)(ap + (size_t)16 * K + 32 * ks);
; #pragma unroll
;         for (int t = 0; t < 4; ++t) { const bf16x8 b = *(const bf16x8*)(bp + (size_t)16 * t * K + 32 * ks);
;             acc[0][t] = __builtin_amdgcn_mfma_f32_16x16x32_bf16(b, a0, acc[0][t], 0, 0, 0); acc[1][t] = __builtin_amdgcn_mfma_f32_16x16x32_bf16(b, a1, acc[1][t], 0, 0, 0); }
;     }
	ds_read_b128 v[90:93], v64 offset:2048
	ds_read_b128 v[94:97], v64 offset:3072
	ds_read_b128 v[98:101], v64 offset:4096
	ds_read_b128 v[102:105], v64 offset:5120
	ds_read_b128 v[106:109], v64 offset:6144
	ds_read_b128 v[110:113], v64 offset:7168
	s_waitcnt lgkmcnt(6)
	v_mfma_f32_16x16x32_bf16 v[30:33], v[74:77], v[66:69], v[30:33]
	v_mfma_f32_16x16x32_bf16 v[14:17], v[74:77], v[70:73], v[14:17]
	v_mfma_f32_16x16x32_bf16 v[26:29], v[78:81], v[66:69], v[26:29]
	v_mfma_f32_16x16x32_bf16 v[10:13], v[78:81], v[70:73], v[10:13]
	v_mfma_f32_16x16x32_bf16 v[22:25], v[82:85], v[66:69], v[22:25]
	v_mfma_f32_16x16x32_bf16 v[6:9], v[82:85], v[70:73], v[6:9]
	v_mfma_f32_16x16x32_bf16 v[18:21], v[86:89], v[66:69], v[18:21]
	v_mfma_f32_16x16x32_bf16 v[2:5], v[86:89], v[70:73], v[2:5]
	s_add_i32 m0, s34, 0x11000
	s_nop 0
	global_load_lds_dwordx4 v[46:47], off
	v_lshl_add_u64 v[46:47], v[46:47], 0, 64
	s_add_i32 m0, s34, 0x11400
	s_nop 0
	global_load_lds_dwordx4 v[44:45], off
	v_lshl_add_u64 v[44:45], v[44:45], 0, 64
	s_add_i32 m0, s34, 0x11800
	s_nop 0
	global_load_lds_dwordx4 v[52:53], off
	v_lshl_add_u64 v[52:53], v[52:53], 0, 64
	s_add_i32 m0, s34, 0x11c00
	s_nop 0
	global_load_lds_dwordx4 v[50:51], off
	v_lshl_add_u64 v[50:51], v[50:51], 0, 64
	s_add_i32 m0, s34, 0x0
	s_nop 0
	global_load_lds_dwordx4 v[42:43], off
	v_lshl_add_u64 v[42:43], v[42:43], 0, 64
	s_add_i32 m0, s34, 0x400
	s_nop 0
	global_load_lds_dwordx4 v[48:49], off
	v_lshl_add_u64 v[48:49], v[48:49], 0, 64
	s_waitcnt vmcnt(4)
	ds_read_b128 v[66:69], v65 offset:0
	ds_read_b128 v[70:73], v65 offset:1024
	ds_read_b128 v[74:77], v65 offset:2048
	ds_read_b128 v[78:81], v65 offset:3072
	ds_read_b128 v[82:85], v65 offset:4096
	ds_read_b128 v[86:89], v65 offset:5120
	s_waitcnt lgkmcnt(6)
	v_mfma_f32_16x16x32_bf16 v[30:33], v[98:101], v[90:93], v[30:33]
	v_mfma_f32_16x16x32_bf16 v[14:17], v[98:101], v[94:97], v[14:17]
	v_mfma_f32_16x16x32_bf16 v[26:29], v[102:105], v[90:93], v[26:29]
	v_mfma_f32_16x16x32_bf16 v[10:13], v[102:105], v[94:97], v[10:13]
	v_mfma_f32_16x16x32_bf16 v[22:25], v[106:109], v[90:93], v[22:25]
	v_mfma_f32_16x16x32_bf16 v[6:9], v[106:109], v[94:97], v[6:9]
	v_mfma_f32_16x16x32_bf16 v[18:21], v[110:113], v[90:93], v[18:21]
	v_mfma_f32_16x16x32_bf16 v[2:5], v[110:113], v[94:97], v[2:5]
	s_add_i32 m0, s34, 0x800
	s_nop 0
	global_load_lds_dwordx4 v[46:47], off
	v_lshl_add_u64 v[46:47], v[46:47], 0, 64
	s_add_i32 m0, s34, 0xc00
	s_nop 0
	global_load_lds_dwordx4 v[44:45], off
	v_lshl_add_u64 v[44:45], v[44:45], 0, 64
	s_add_i32 m0, s34, 0x1000
	s_nop 0
	global_load_lds_dwordx4 v[52:53], off
	v_lshl_add_u64 v[52:53], v[52:53], 0, 64
	s_add_i32 m0, s34, 0x1400
	s_nop 0
	global_load_lds_dwordx4 v[50:51], off
	v_lshl_add_u64 v[50:51], v[50:51], 0, 64
	s_add_i32 m0, s34, 0x1800
	s_nop 0
	global_load_lds_dwordx4 v[42:43], off
	v_lshl_add_u64 v[42:43], v[42:43], 0, 64
	s_add_i32 m0, s34, 0x1c00
	s_nop 0
	global_load_lds_dwordx4 v[48:49], off
	v_lshl_add_u64 v[48:49], v[48:49], 0, 64
	s_waitcnt vmcnt(4)
	ds_read_b128 v[90:93], v65 offset:6144
	ds_read_b128 v[94:97], v65 offset:7168
	ds_read_b128 v[98:101], v64 offset:0
	ds_read_b128 v[102:105], v64 offset:1024
	ds_read_b128 v[106:109], v64 offset:2048
	ds_read_b128 v[110:113], v64 offset:3072
	s_waitcnt lgkmcnt(6)
	v_mfma_f32_16x16x32_bf16 v[30:33], v[74:77], v[66:69], v[30:33]
	v_mfma_f32_16x16x32_bf16 v[14:17], v[74:77], v[70:73], v[14:17]
	v_mfma_f32_16x16x32_bf16 v[26:29], v[78:81], v[66:69], v[26:29]
	v_mfma_f32_16x16x32_bf16 v[10:13], v[78:81], v[70:73], v[10:13]
	v_mfma_f32_16x16x32_bf16 v[22:25], v[82:85], v[66:69], v[22:25]
	v_mfma_f32_16x16x32_bf16 v[6:9], v[82:85], v[70:73], v[6:9]
	v_mfma_f32_16x16x32_bf16 v[18:21], v[86:89], v[66:69], v[18:21]
	v_mfma_f32_16x16x32_bf16 v[2:5], v[86:89], v[70:73], v[2:5]
	s_add_i32 m0, s34, 0x10000
	s_nop 0
	global_load_lds_dwordx4 v[46:47], off
	v_lshl_add_u64 v[46:47], v[46:47], 0, 64
	s_add_i32 m0, s34, 0x10400
	s_nop 0
	global_load_lds_dwordx4 v[44:45], off
	v_lshl_add_u64 v[44:45], v[44:45], 0, 64
	s_add_i32 m0, s34, 0x10800
	s_nop 0
	global_load_lds_dwordx4 v[52:53], off
	v_lshl_add_u64 v[52:53], v[52:53], 0, 64
	s_add_i32 m0, s34, 0x10c00
	s_nop 0
	global_load_lds_dwordx4 v[50:51], off
	v_lshl_add_u64 v[50:51], v[50:51], 0, 64
	s_add_i32 m0, s34, 0x11000
	s_nop 0
	global_load_lds_dwordx4 v[42:43], off
	v_lshl_add_u64 v[42:43], v[42:43], 0, 64
	s_add_i32 m0, s34, 0x11400
	s_nop 0
	global_load_lds_dwordx4 v[48:49], off
	v_lshl_add_u64 v[48:49], v[48:49], 0, 64
	s_waitcnt vmcnt(4)
	ds_read_b128 v[66:69], v64 offset:4096
	ds_read_b128 v[70:73], v64 offset:5120
	ds_read_b128 v[74:77], v64 offset:6144
	ds_read_b128 v[78:81], v64 offset:7168
	ds_read_b128 v[82:85], v65 offset:0
	ds_read_b128 v[86:89], v65 offset:1024
	s_waitcnt lgkmcnt(6)
	v_mfma_f32_16x16x32_bf16 v[30:33], v[98:101], v[90:93], v[30:33]
	v_mfma_f32_16x16x32_bf16 v[14:17], v[98:101], v[94:97], v[14:17]
	v_mfma_f32_16x16x32_bf16 v[26:29], v[102:105], v[90:93], v[26:29]
	v_mfma_f32_16x16x32_bf16 v[10:13], v[102:105], v[94:97], v[10:13]
	v_mfma_f32_16x16x32_bf16 v[22:25], v[106:109], v[90:93], v[22:25]
	v_mfma_f32_16x16x32_bf16 v[6:9], v[106:109], v[94:97], v[6:9]
	v_mfma_f32_16x16x32_bf16 v[18:21], v[110:113], v[90:93], v[18:21]
	v_mfma_f32_16x16x32_bf16 v[2:5], v[110:113], v[94:97], v[2:5]
	s_add_i32 m0, s34, 0x11800
	s_nop 0
	global_load_lds_dwordx4 v[46:47], off
	v_lshl_add_u64 v[46:47], v[46:47], 0, 64
	s_add_i32 m0, s34, 0x11c00
	s_nop 0
	global_load_lds_dwordx4 v[44:45], off
	v_lshl_add_u64 v[44:45], v[44:45], 0, 64
	s_add_i32 m0, s34, 0x0
	s_nop 0
	global_load_lds_dwordx4 v[52:53], off
	v_lshl_add_u64 v[52:53], v[52:53], 0, 64
	s_add_i32 m0, s34, 0x400
	s_nop 0
	global_load_lds_dwordx4 v[50:51], off
	v_lshl_add_u64 v[50:51], v[50:51], 0, 64
	s_add_i32 m0, s34, 0x800
	s_nop 0
	global_load_lds_dwordx4 v[42:43], off
	v_lshl_add_u64 v[42:43], v[42:43], 0, 64
	s_add_i32 m0, s34, 0xc00
	s_nop 0
	global_load_lds_dwordx4 v[48:49], off
	v_lshl_add_u64 v[48:49], v[48:49], 0, 64
	s_waitcnt vmcnt(4)
; __device__ __forceinline__ void small_gemm_res(LAS unsigned char* lds, const bf16_t* A, const bf16_t* Bt, int K, int unit, bf16_t* XB, float* SS, float sc) {
;     ...
;     const bf16_t* ap = A + (size_t)(row0 + li) * K + 8 * g4 + 32 * wave * KS;
;     const bf16_t* bp = Bt + (size_t)(col0 + li) * K + 8 * g4 + 32 * wave * KS;
; #pragma unroll 6
;     for (int ks = 0; ks < KS; ++ks) {
;         const bf16x8 a0 = *(const bf16x8*)(ap + 32 * ks), a1 = *(const bf16x8*)(ap + (size_t)16 * K + 32 * ks);
; #pragma unroll
;         for (int t = 0; t < 4; ++t) { const bf16x8 b = *(const bf16x8*)(bp + (size_t)16 * t * K + 32 * ks);
;             acc[0][t] = __builtin_amdgcn_mfma_f32_16x16x32_bf16(b, a0, acc[0][t], 0, 0, 0); acc[1][t] = __builtin_amdgcn_mfma_f32_16x16x32_bf16(b, a1, acc[1][t], 0, 0, 0); }
;     }
	ds_read_b128 v[90:93], v65 offset:2048
	ds_read_b128 v[94:97], v65 offset:3072
	ds_read_b128 v[98:101], v65 offset:4096
	ds_read_b128 v[102:105], v65 offset:5120
	ds_read_b128 v[106:109], v65 offset:6144
	ds_read_b128 v[110:113], v65 offset:7168
	s_waitcnt lgkmcnt(6)
	v_mfma_f32_16x16x32_bf16 v[30:33], v[74:77], v[66:69], v[30:33]
	v_mfma_f32_16x16x32_bf16 v[14:17], v[74:77], v[70:73], v[14:17]
	v_mfma_f32_16x16x32_bf16 v[26:29], v[78:81], v[66:69], v[26:29]
	v_mfma_f32_16x16x32_bf16 v[10:13], v[78:81], v[70:73], v[10:13]
	v_mfma_f32_16x16x32_bf16 v[22:25], v[82:85], v[66:69], v[22:25]
	v_mfma_f32_16x16x32_bf16 v[6:9], v[82:85], v[70:73], v[6:9]
	v_mfma_f32_16x16x32_bf16 v[18:21], v[86:89], v[66:69], v[18:21]
	v_mfma_f32_16x16x32_bf16 v[2:5], v[86:89], v[70:73], v[2:5]
	s_add_i32 m0, s34, 0x1000
	s_nop 0
	global_load_lds_dwordx4 v[46:47], off
	v_lshl_add_u64 v[46:47], v[46:47], 0, 64
	s_add_i32 m0, s34, 0x1400
	s_nop 0
	global_load_lds_dwordx4 v[44:45], off
	v_lshl_add_u64 v[44:45], v[44:45], 0, 64
	s_add_i32 m0, s34, 0x1800
	s_nop 0
	global_load_lds_dwordx4 v[52:53], off
	v_lshl_add_u64 v[52:53], v[52:53], 0, 64
	s_add_i32 m0, s34, 0x1c00
	s_nop 0
	global_load_lds_dwordx4 v[50:51], off
	v_lshl_add_u64 v[50:51], v[50:51], 0, 64
	s_add_i32 m0, s34, 0x10000
	s_nop 0
	global_load_lds_dwordx4 v[42:43], off
	v_lshl_add_u64 v[42:43], v[42:43], 0, 64
	s_add_i32 m0, s34, 0x10400
	s_nop 0
	global_load_lds_dwordx4 v[48:49], off
	v_lshl_add_u64 v[48:49], v[48:49], 0, 64
	s_waitcnt vmcnt(4)
	ds_read_b128 v[66:69], v64 offset:0
	ds_read_b128 v[70:73], v64 offset:1024
	ds_read_b128 v[74:77], v64 offset:2048
	ds_read_b128 v[78:81], v64 offset:3072
	ds_read_b128 v[82:85], v64 offset:4096
	ds_read_b128 v[86:89], v64 offset:5120
	s_waitcnt lgkmcnt(6)
	v_mfma_f32_16x16x32_bf16 v[30:33], v[98:101], v[90:93], v[30:33]
	v_mfma_f32_16x16x32_bf16 v[14:17], v[98:101], v[94:97], v[14:17]
	v_mfma_f32_16x16x32_bf16 v[26:29], v[102:105], v[90:93], v[26:29]
	v_mfma_f32_16x16x32_bf16 v[10:13], v[102:105], v[94:97], v[10:13]
	v_mfma_f32_16x16x32_bf16 v[22:25], v[106:109], v[90:93], v[22:25]
	v_mfma_f32_16x16x32_bf16 v[6:9], v[106:109], v[94:97], v[6:9]
	v_mfma_f32_16x16x32_bf16 v[18:21], v[110:113], v[90:93], v[18:21]
	v_mfma_f32_16x16x32_bf16 v[2:5], v[110:113], v[94:97], v[2:5]
	s_add_i32 m0, s34, 0x10800
	s_nop 0
	global_load_lds_dwordx4 v[46:47], off
	v_lshl_add_u64 v[46:47], v[46:47], 0, 64
	s_add_i32 m0, s34, 0x10c00
	s_nop 0
	global_load_lds_dwordx4 v[44:45], off
	v_lshl_add_u64 v[44:45], v[44:45], 0, 64
	s_add_i32 m0, s34, 0x11000
	s_nop 0
	global_load_lds_dwordx4 v[52:53], off
	v_lshl_add_u64 v[52:53], v[52:53], 0, 64
	s_add_i32 m0, s34, 0x11400
	s_nop 0
	global_load_lds_dwordx4 v[50:51], off
	v_lshl_add_u64 v[50:51], v[50:51], 0, 64
	s_add_i32 m0, s34, 0x11800
	s_nop 0
	global_load_lds_dwordx4 v[42:43], off
	v_lshl_add_u64 v[42:43], v[42:43], 0, 64
	s_add_i32 m0, s34, 0x11c00
	s_nop 0
	global_load_lds_dwordx4 v[48:49], off
	v_lshl_add_u64 v[48:49], v[48:49], 0, 64
	s_waitcnt vmcnt(4)
	ds_read_b128 v[90:93], v64 offset:6144
	ds_read_b128 v[94:97], v64 offset:7168
	ds_read_b128 v[98:101], v65 offset:0
	ds_read_b128 v[102:105], v65 offset:1024
	ds_read_b128 v[106:109], v65 offset:2048
	ds_read_b128 v[110:113], v65 offset:3072
	s_waitcnt lgkmcnt(6)
	v_mfma_f32_16x16x32_bf16 v[30:33], v[74:77], v[66:69], v[30:33]
	v_mfma_f32_16x16x32_bf16 v[14:17], v[74:77], v[70:73], v[14:17]
	v_mfma_f32_16x16x32_bf16 v[26:29], v[78:81], v[66:69], v[26:29]
	v_mfma_f32_16x16x32_bf16 v[10:13], v[78:81], v[70:73], v[10:13]
	v_mfma_f32_16x16x32_bf16 v[22:25], v[82:85], v[66:69], v[22:25]
	v_mfma_f32_16x16x32_bf16 v[6:9], v[82:85], v[70:73], v[6:9]
	v_mfma_f32_16x16x32_bf16 v[18:21], v[86:89], v[66:69], v[18:21]
	v_mfma_f32_16x16x32_bf16 v[2:5], v[86:89], v[70:73], v[2:5]
	s_add_i32 m0, s34, 0x0
	s_nop 0
	global_load_lds_dwordx4 v[46:47], off
	v_lshl_add_u64 v[46:47], v[46:47], 0, 64
	s_add_i32 m0, s34, 0x400
	s_nop 0
	global_load_lds_dwordx4 v[44:45], off
	v_lshl_add_u64 v[44:45], v[44:45], 0, 64
	s_waitcnt vmcnt(0)
	ds_read_b128 v[66:69], v65 offset:4096
	ds_read_b128 v[70:73], v65 offset:5120
	ds_read_b128 v[74:77], v65 offset:6144
	ds_read_b128 v[78:81], v65 offset:7168
	ds_read_b128 v[82:85], v64 offset:0
	ds_read_b128 v[86:89], v64 offset:1024
	s_waitcnt lgkmcnt(6)
	v_mfma_f32_16x16x32_bf16 v[30:33], v[98:101], v[90:93], v[30:33]
	v_mfma_f32_16x16x32_bf16 v[14:17], v[98:101], v[94:97], v[14:17]
	v_mfma_f32_16x16x32_bf16 v[26:29], v[102:105], v[90:93], v[26:29]
	v_mfma_f32_16x16x32_bf16 v[10:13], v[102:105], v[94:97], v[10:13]
	v_mfma_f32_16x16x32_bf16 v[22:25], v[106:109], v[90:93], v[22:25]
	v_mfma_f32_16x16x32_bf16 v[6:9], v[106:109], v[94:97], v[6:9]
	v_mfma_f32_16x16x32_bf16 v[18:21], v[110:113], v[90:93], v[18:21]
	v_mfma_f32_16x16x32_bf16 v[2:5], v[110:113], v[94:97], v[2:5]
	s_waitcnt lgkmcnt(0)
	v_mfma_f32_16x16x32_bf16 v[30:33], v[74:77], v[66:69], v[30:33]
	v_mfma_f32_16x16x32_bf16 v[14:17], v[74:77], v[70:73], v[14:17]
	v_mfma_f32_16x16x32_bf16 v[26:29], v[78:81], v[66:69], v[26:29]
	v_mfma_f32_16x16x32_bf16 v[10:13], v[78:81], v[70:73], v[10:13]
	v_mfma_f32_16x16x32_bf16 v[22:25], v[82:85], v[66:69], v[22:25]
	v_mfma_f32_16x16x32_bf16 v[6:9], v[82:85], v[70:73], v[6:9]
	v_mfma_f32_16x16x32_bf16 v[18:21], v[86:89], v[66:69], v[18:21]
	v_mfma_f32_16x16x32_bf16 v[2:5], v[86:89], v[70:73], v[2:5]
	s_branch .Lsgr_done
; __device__ __forceinline__ void small_gemm_res(LAS unsigned char* lds, const bf16_t* A, const bf16_t* Bt, int K, int unit, bf16_t* XB, float* SS, float sc) {
;     ...
;     const bf16_t* ap = A + (size_t)(row0 + li) * K + 8 * g4 + 32 * wave * KS;
;     const bf16_t* bp = Bt + (size_t)(col0 + li) * K + 8 * g4 + 32 * wave * KS;
; #pragma unroll 6
;     for (int ks = 0; ks < KS; ++ks) {
;         const bf16x8 a0 = *(const bf16x8*)(ap + 32 * ks), a1 = *(const bf16x8*)(ap + (size_t)16 * K + 32 * ks);
; #pragma unroll
;         for (int t = 0; t < 4; ++t) { const bf16x8 b = *(const bf16x8*)(bp + (size_t)16 * t * K + 32 * ks);
;             acc[0][t] = __builtin_amdgcn_mfma_f32_16x16x32_bf16(b, a0, acc[0][t], 0, 0, 0); acc[1][t] = __builtin_amdgcn_mfma_f32_16x16x32_bf16(b, a1, acc[1][t], 0, 0, 0); }
;     }
.Lsgr_k4:
	v_bfe_u32 v62, v208, 2, 4
	v_and_b32_e32 v63, 3, v208
	v_sub_u32_e32 v62, v62, v58
	v_mul_lo_u32 v62, v62, s7
	v_lshlrev_b32_e32 v63, 4, v63
	v_sub_u32_e32 v63, v63, v40
	v_lshl_add_u32 v62, v62, 1, v63
	v_ashrrev_i32_e32 v63, 31, v62
	v_lshl_add_u64 v[52:53], v[52:53], 0, s[28:29]
	v_lshl_add_u64 v[52:53], v[52:53], 0, v[62:63]
	v_lshl_add_u64 v[50:51], v[50:51], 0, s[28:29]
	v_lshl_add_u64 v[50:51], v[50:51], 0, v[62:63]
	v_lshl_add_u64 v[42:43], v[42:43], 0, s[28:29]
	v_lshl_add_u64 v[42:43], v[42:43], 0, v[62:63]
	v_lshl_add_u64 v[48:49], v[48:49], 0, s[28:29]
	v_lshl_add_u64 v[48:49], v[48:49], 0, v[62:63]
	v_lshl_add_u64 v[46:47], v[46:47], 0, s[28:29]
	v_lshl_add_u64 v[46:47], v[46:47], 0, v[62:63]
	v_lshl_add_u64 v[44:45], v[44:45], 0, s[28:29]
	v_lshl_add_u64 v[44:45], v[44:45], 0, v[62:63]
	s_lshl_b32 s34, s31, 8
	v_lshl_add_u32 v64, v58, 6, v40
	v_add_u32_e32 v64, s34, v64
	v_add_u32_e32 v65, 0x10000, v64
	s_add_i32 m0, s34, 0x0
	s_nop 0
	global_load_lds_dwordx4 v[52:53], off
	v_lshl_add_u64 v[52:53], v[52:53], 0, 64
	s_add_i32 m0, s34, 0x400
	s_nop 0
	global_load_lds_dwordx4 v[50:51], off
	v_lshl_add_u64 v[50:51], v[50:51], 0, 64
	s_add_i32 m0, s34, 0x800
	s_nop 0
	global_load_lds_dwordx4 v[42:43], off
	v_lshl_add_u64 v[42:43], v[42:43], 0, 64
	s_add_i32 m0, s34, 0xc00
	s_nop 0
	global_load_lds_dwordx4 v[48:49], off
	v_lshl_add_u64 v[48:49], v[48:49], 0, 64
	s_add_i32 m0, s34, 0x1000
	s_nop 0
	global_load_lds_dwordx4 v[46:47], off
	v_lshl_add_u64 v[46:47], v[46:47], 0, 64
	s_add_i32 m0, s34, 0x1400
	s_nop 0
	global_load_lds_dwordx4 v[44:45], off
	v_lshl_add_u64 v[44:45], v[44:45], 0, 64
	s_add_i32 m0, s34, 0x1800
	s_nop 0
	global_load_lds_dwordx4 v[52:53], off
	v_lshl_add_u64 v[52:53], v[52:53], 0, 64
	s_add_i32 m0, s34, 0x1c00
	s_nop 0
	global_load_lds_dwordx4 v[50:51], off
	v_lshl_add_u64 v[50:51], v[50:51], 0, 64
	s_add_i32 m0, s34, 0x10000
	s_nop 0
	global_load_lds_dwordx4 v[42:43], off
	v_lshl_add_u64 v[42:43], v[42:43], 0, 64
	s_add_i32 m0, s34, 0x10400
	s_nop 0
	global_load_lds_dwordx4 v[48:49], off
	v_lshl_add_u64 v[48:49], v[48:49], 0, 64
	s_add_i32 m0, s34, 0x10800
	s_nop 0
	global_load_lds_dwordx4 v[46:47], off
	v_lshl_add_u64 v[46:47], v[46:47], 0, 64
	s_add_i32 m0, s34, 0x10c00
	s_nop 0
	global_load_lds_dwordx4 v[44:45], off
	v_lshl_add_u64 v[44:45], v[44:45], 0, 64
	s_add_i32 m0, s34, 0x11000
	s_nop 0
	global_load_lds_dwordx4 v[52:53], off
	v_lshl_add_u64 v[52:53], v[52:53], 0, 64
	s_add_i32 m0, s34, 0x11400
	s_nop 0
	global_load_lds_dwordx4 v[50:51], off
	v_lshl_add_u64 v[50:51], v[50:51], 0, 64
	s_add_i32 m0, s34, 0x11800
	s_nop 0
	global_load_lds_dwordx4 v[42:43], off
	v_lshl_add_u64 v[42:43], v[42:43], 0, 64
	s_add_i32 m0, s34, 0x11c00
	s_nop 0
	global_load_lds_dwordx4 v[48:49], off
	v_lshl_add_u64 v[48:49], v[48:49], 0, 64
	s_waitcnt vmcnt(10)
	ds_read_b128 v[66:69], v64 offset:0
	ds_read_b128 v[70:73], v64 offset:1024
	ds_read_b128 v[74:77], v64 offset:2048
	ds_read_b128 v[78:81], v64 offset:3072
	ds_read_b128 v[82:85], v64 offset:4096
	ds_read_b128 v[86:89], v64 offset:5120
	s_waitcnt vmcnt(4)
	ds_read_b128 v[90:93], v64 offset:6144
	ds_read_b128 v[94:97], v64 offset:7168
	ds_read_b128 v[98:101], v65 offset:0
	ds_read_b128 v[102:105], v65 offset:1024
	ds_read_b128 v[106:109], v65 offset:2048
	ds_read_b128 v[110:113], v65 offset:3072
	s_waitcnt lgkmcnt(6)
	v_mfma_f32_16x16x32_bf16 v[30:33], v[74:77], v[66:69], v[30:33]
	v_mfma_f32_16x16x32_bf16 v[14:17], v[74:77], v[70:73], v[14:17]
	v_mfma_f32_16x16x32_bf16 v[26:29], v[78:81], v[66:69], v[26:29]
	v_mfma_f32_16x16x32_bf16 v[10:13], v[78:81], v[70:73], v[10:13]
	v_mfma_f32_16x16x32_bf16 v[22:25], v[82:85], v[66:69], v[22:25]
	v_mfma_f32_16x16x32_bf16 v[6:9], v[82:85], v[70:73], v[6:9]
	v_mfma_f32_16x16x32_bf16 v[18:21], v[86:89], v[66:69], v[18:21]
	v_mfma_f32_16x16x32_bf16 v[2:5], v[86:89], v[70:73], v[2:5]
	s_add_i32 m0, s34, 0x0
	s_nop 0
	global_load_lds_dwordx4 v[46:47], off
	v_lshl_add_u64 v[46:47], v[46:47], 0, 64
	s_add_i32 m0, s34, 0x400
	s_nop 0
	global_load_lds_dwordx4 v[44:45], off
	v_lshl_add_u64 v[44:45], v[44:45], 0, 64
	s_add_i32 m0, s34, 0x800
	s_nop 0
	global_load_lds_dwordx4 v[52:53], off
	v_lshl_add_u64 v[52:53], v[52:53], 0, 64
	s_add_i32 m0, s34, 0xc00
	s_nop 0
	global_load_lds_dwordx4 v[50:51], off
	v_lshl_add_u64 v[50:51], v[50:51], 0, 64
	s_add_i32 m0, s34, 0x1000
	s_nop 0
	global_load_lds_dwordx4 v[42:43], off
	v_lshl_add_u64 v[42:43], v[42:43], 0, 64
	s_add_i32 m0, s34, 0x1400
	s_nop 0
	global_load_lds_dwordx4 v[48:49], off
	v_lshl_add_u64 v[48:49], v[48:49], 0, 64
	s_waitcnt vmcnt(4)
	ds_read_b128 v[66:69], v65 offset:4096
	ds_read_b128 v[70:73], v65 offset:5120
	ds_read_b128 v[74:77], v65 offset:6144
	ds_read_b128 v[78:81], v65 offset:7168
	ds_read_b128 v[82:85], v64 offset:0
	ds_read_b128 v[86:89], v64 offset:1024
	s_waitcnt lgkmcnt(6)
	v_mfma_f32_16x16x32_bf16 v[30:33], v[98:101], v[90:93], v[30:33]
	v_mfma_f32_16x16x32_bf16 v[14:17], v[98:101], v[94:97], v[14:17]
	v_mfma_f32_16x16x32_bf16 v[26:29], v[102:105], v[90:93], v[26:29]
	v_mfma_f32_16x16x32_bf16 v[10:13], v[102:105], v[94:97], v[10:13]
	v_mfma_f32_16x16x32_bf16 v[22:25], v[106:109], v[90:93], v[22:25]
	v_mfma_f32_16x16x32_bf16 v[6:9], v[106:109], v[94:97], v[6:9]
	v_mfma_f32_16x16x32_bf16 v[18:21], v[110:113], v[90:93], v[18:21]
	v_mfma_f32_16x16x32_bf16 v[2:5], v[110:113], v[94:97], v[2:5]
	s_add_i32 m0, s34, 0x1800
	s_nop 0
	global_load_lds_dwordx4 v[46:47], off
	v_lshl_add_u64 v[46:47], v[46:47], 0, 64
	s_add_i32 m0, s34, 0x1c00
	s_nop 0
	global_load_lds_dwordx4 v[44:45], off
	v_lshl_add_u64 v[44:45], v[44:45], 0, 64
	s_waitcnt vmcnt(0)
	ds_read_b128 v[90:93], v64 offset:2048
	ds_read_b128 v[94:97], v64 offset:3072
	ds_read_b128 v[98:101], v64 offset:4096
	ds_read_b128 v[102:105], v64 offset:5120
	ds_read_b128 v[106:109], v64 offset:6144
	ds_read_b128 v[110:113], v64 offset:7168
	s_waitcnt lgkmcnt(6)
	v_mfma_f32_16x16x32_bf16 v[30:33], v[74:77], v[66:69], v[30:33]
	v_mfma_f32_16x16x32_bf16 v[14:17], v[74:77], v[70:73], v[14:17]
	v_mfma_f32_16x16x32_bf16 v[26:29], v[78:81], v[66:69], v[26:29]
	v_mfma_f32_16x16x32_bf16 v[10:13], v[78:81], v[70:73], v[10:13]
	v_mfma_f32_16x16x32_bf16 v[22:25], v[82:85], v[66:69], v[22:25]
	v_mfma_f32_16x16x32_bf16 v[6:9], v[82:85], v[70:73], v[6:9]
	v_mfma_f32_16x16x32_bf16 v[18:21], v[86:89], v[66:69], v[18:21]
	v_mfma_f32_16x16x32_bf16 v[2:5], v[86:89], v[70:73], v[2:5]
	s_waitcnt lgkmcnt(0)
	v_mfma_f32_16x16x32_bf16 v[30:33], v[98:101], v[90:93], v[30:33]
	v_mfma_f32_16x16x32_bf16 v[14:17], v[98:101], v[94:97], v[14:17]
	v_mfma_f32_16x16x32_bf16 v[26:29], v[102:105], v[90:93], v[26:29]
	v_mfma_f32_16x16x32_bf16 v[10:13], v[102:105], v[94:97], v[10:13]
	v_mfma_f32_16x16x32_bf16 v[22:25], v[106:109], v[90:93], v[22:25]
	v_mfma_f32_16x16x32_bf16 v[6:9], v[106:109], v[94:97], v[6:9]
	v_mfma_f32_16x16x32_bf16 v[18:21], v[110:113], v[90:93], v[18:21]
	v_mfma_f32_16x16x32_bf16 v[2:5], v[110:113], v[94:97], v[2:5]
